# A16: A13 + scan issues the next token's two v reads behind the last reduction level (light steps)
# baseline (speedup 1.0000x reference)
.Lrw_scan_loop:
	s_and_b32 s2, s8, 1
	s_mul_i32 s3, s2, 0xe000
	s_lshl_b32 s2, s2, 12
	v_add_u32_e32 v195, s3, v103
	v_add_u32_e32 v33, s3, v38
	v_add_u32_e32 v196, s3, v75
	v_add_u32_e32 v36, s3, v37
	v_add_u32_e32 v102, s2, v76
	ds_read_b128 v[140:143], v195 offset:0
	ds_read_b128 v[152:155], v195 offset:8192
	ds_read_b128 v[176:179], v195 offset:16384
	ds_read_b128 v[84:87], v195 offset:32768
	ds_read_b64 v[4:5], v196 offset:0
	ds_read_b32 v6, v36 offset:0
	ds_read_b128 v[144:147], v195 offset:256
	ds_read_b128 v[156:159], v195 offset:8448
	ds_read_b128 v[180:183], v195 offset:16640
	ds_read_b128 v[88:91], v195 offset:33024
	s_waitcnt lgkmcnt(4)
	v_pk_mul_f32 v[46:47], v[24:25], v[140:141] op_sel_hi:[0,1]
	v_pk_mul_f32 v[34:35], v[20:21], v[140:141] op_sel_hi:[0,1]
	v_pk_fma_f32 v[46:47], v[24:25], v[142:143], v[46:47] op_sel:[1,0,0] op_sel_hi:[1,1,1]
	v_pk_fma_f32 v[34:35], v[20:21], v[142:143], v[34:35] op_sel:[1,0,0] op_sel_hi:[1,1,1]
	v_pk_fma_f32 v[46:47], v[26:27], v[152:153], v[46:47] op_sel_hi:[0,1,1]
	v_pk_fma_f32 v[34:35], v[22:23], v[152:153], v[34:35] op_sel_hi:[0,1,1]
	v_pk_fma_f32 v[46:47], v[26:27], v[154:155], v[46:47] op_sel:[1,0,0] op_sel_hi:[1,1,1]
	v_pk_fma_f32 v[34:35], v[22:23], v[154:155], v[34:35] op_sel:[1,0,0] op_sel_hi:[1,1,1]
	v_pk_fma_f32 v[20:21], v[176:177], v[4:5], v[20:21] op_sel_hi:[1,0,1]
	v_add_f32_dpp v28, v46, v34 row_half_mirror row_mask:0xf bank_mask:0xf
	v_add_f32_dpp v32, v47, v35 row_half_mirror row_mask:0xf bank_mask:0xf
	v_pk_fma_f32 v[22:23], v[178:179], v[4:5], v[22:23] op_sel_hi:[1,0,1]
	v_add_f32_dpp v28, v28, v28 row_ror:8 row_mask:0xf bank_mask:0xf
	v_add_f32_dpp v32, v32, v32 row_ror:8 row_mask:0xf bank_mask:0xf
	v_pk_fma_f32 v[24:25], v[176:177], v[6:7], v[24:25] op_sel_hi:[1,0,1]
	v_add_f32_dpp v28, v28, v28 quad_perm:[1,0,3,2] row_mask:0xf bank_mask:0xf
	v_add_f32_dpp v32, v32, v32 quad_perm:[1,0,3,2] row_mask:0xf bank_mask:0xf
	v_pk_fma_f32 v[26:27], v[178:179], v[6:7], v[26:27] op_sel_hi:[1,0,1]
	v_add_f32_dpp v28, v28, v28 quad_perm:[2,3,0,1] row_mask:0xf bank_mask:0xf
	v_add_f32_dpp v32, v32, v32 quad_perm:[2,3,0,1] row_mask:0xf bank_mask:0xf
	ds_read_b64 v[8:9], v196 offset:512
	ds_read_b32 v10, v36 offset:512
	v_add_f32_e32 v39, v32, v5
	v_mov_b32_dpp v30, v28 row_half_mirror row_mask:0xf bank_mask:0xf
	v_pk_fma_f32 v[20:21], v[84:85], v[28:29], v[20:21] op_sel_hi:[1,0,1] neg_lo:[0,1,0] neg_hi:[0,1,0]
	v_pk_fma_f32 v[22:23], v[86:87], v[28:29], v[22:23] op_sel_hi:[1,0,1] neg_lo:[0,1,0] neg_hi:[0,1,0]
	v_pk_fma_f32 v[24:25], v[84:85], v[30:31], v[24:25] op_sel_hi:[1,0,1] neg_lo:[0,1,0] neg_hi:[0,1,0]
	v_pk_fma_f32 v[26:27], v[86:87], v[30:31], v[26:27] op_sel_hi:[1,0,1] neg_lo:[0,1,0] neg_hi:[0,1,0]
	ds_write_b32 v102, v39 offset:0
	ds_read_b128 v[140:143], v195 offset:512
	ds_read_b128 v[152:155], v195 offset:8704
	ds_read_b128 v[176:179], v195 offset:16896
	ds_read_b128 v[84:87], v195 offset:33280
	s_waitcnt lgkmcnt(5)
	v_pk_mul_f32 v[46:47], v[24:25], v[144:145] op_sel_hi:[0,1]
	v_pk_mul_f32 v[34:35], v[20:21], v[144:145] op_sel_hi:[0,1]
	v_pk_fma_f32 v[46:47], v[24:25], v[146:147], v[46:47] op_sel:[1,0,0] op_sel_hi:[1,1,1]
	v_pk_fma_f32 v[34:35], v[20:21], v[146:147], v[34:35] op_sel:[1,0,0] op_sel_hi:[1,1,1]
	v_pk_fma_f32 v[46:47], v[26:27], v[156:157], v[46:47] op_sel_hi:[0,1,1]
	v_pk_fma_f32 v[34:35], v[22:23], v[156:157], v[34:35] op_sel_hi:[0,1,1]
	v_pk_fma_f32 v[46:47], v[26:27], v[158:159], v[46:47] op_sel:[1,0,0] op_sel_hi:[1,1,1]
	v_pk_fma_f32 v[34:35], v[22:23], v[158:159], v[34:35] op_sel:[1,0,0] op_sel_hi:[1,1,1]
	v_pk_fma_f32 v[20:21], v[180:181], v[8:9], v[20:21] op_sel_hi:[1,0,1]
	v_add_f32_dpp v28, v46, v34 row_half_mirror row_mask:0xf bank_mask:0xf
	v_add_f32_dpp v32, v47, v35 row_half_mirror row_mask:0xf bank_mask:0xf
	v_pk_fma_f32 v[22:23], v[182:183], v[8:9], v[22:23] op_sel_hi:[1,0,1]
	v_add_f32_dpp v28, v28, v28 row_ror:8 row_mask:0xf bank_mask:0xf
	v_add_f32_dpp v32, v32, v32 row_ror:8 row_mask:0xf bank_mask:0xf
	v_pk_fma_f32 v[24:25], v[180:181], v[10:11], v[24:25] op_sel_hi:[1,0,1]
	v_add_f32_dpp v28, v28, v28 quad_perm:[1,0,3,2] row_mask:0xf bank_mask:0xf
	v_add_f32_dpp v32, v32, v32 quad_perm:[1,0,3,2] row_mask:0xf bank_mask:0xf
	v_pk_fma_f32 v[26:27], v[182:183], v[10:11], v[26:27] op_sel_hi:[1,0,1]
	v_add_f32_dpp v28, v28, v28 quad_perm:[2,3,0,1] row_mask:0xf bank_mask:0xf
	v_add_f32_dpp v32, v32, v32 quad_perm:[2,3,0,1] row_mask:0xf bank_mask:0xf
	ds_read_b64 v[4:5], v196 offset:1024
	ds_read_b32 v6, v36 offset:1024
	v_add_f32_e32 v39, v32, v9
	v_mov_b32_dpp v30, v28 row_half_mirror row_mask:0xf bank_mask:0xf
	v_pk_fma_f32 v[20:21], v[88:89], v[28:29], v[20:21] op_sel_hi:[1,0,1] neg_lo:[0,1,0] neg_hi:[0,1,0]
	v_pk_fma_f32 v[22:23], v[90:91], v[28:29], v[22:23] op_sel_hi:[1,0,1] neg_lo:[0,1,0] neg_hi:[0,1,0]
	v_pk_fma_f32 v[24:25], v[88:89], v[30:31], v[24:25] op_sel_hi:[1,0,1] neg_lo:[0,1,0] neg_hi:[0,1,0]
	v_pk_fma_f32 v[26:27], v[90:91], v[30:31], v[26:27] op_sel_hi:[1,0,1] neg_lo:[0,1,0] neg_hi:[0,1,0]
	ds_write_b32 v102, v39 offset:128
	ds_read_b128 v[144:147], v195 offset:768
	ds_read_b128 v[156:159], v195 offset:8960
	ds_read_b128 v[168:171], v195 offset:25344
	ds_read_b128 v[180:183], v195 offset:17152
	ds_read_b128 v[88:91], v195 offset:33536
	s_waitcnt lgkmcnt(6)
	v_pk_mul_f32 v[46:47], v[24:25], v[140:141] op_sel_hi:[0,1]
	v_pk_mul_f32 v[34:35], v[20:21], v[140:141] op_sel_hi:[0,1]
	v_pk_fma_f32 v[46:47], v[24:25], v[142:143], v[46:47] op_sel:[1,0,0] op_sel_hi:[1,1,1]
	v_pk_fma_f32 v[34:35], v[20:21], v[142:143], v[34:35] op_sel:[1,0,0] op_sel_hi:[1,1,1]
	v_pk_fma_f32 v[46:47], v[26:27], v[152:153], v[46:47] op_sel_hi:[0,1,1]
	v_pk_fma_f32 v[34:35], v[22:23], v[152:153], v[34:35] op_sel_hi:[0,1,1]
	v_pk_fma_f32 v[46:47], v[26:27], v[154:155], v[46:47] op_sel:[1,0,0] op_sel_hi:[1,1,1]
	v_pk_fma_f32 v[34:35], v[22:23], v[154:155], v[34:35] op_sel:[1,0,0] op_sel_hi:[1,1,1]
	v_pk_fma_f32 v[20:21], v[176:177], v[4:5], v[20:21] op_sel_hi:[1,0,1]
	v_add_f32_dpp v28, v46, v34 row_half_mirror row_mask:0xf bank_mask:0xf
	v_add_f32_dpp v32, v47, v35 row_half_mirror row_mask:0xf bank_mask:0xf
	v_pk_fma_f32 v[22:23], v[178:179], v[4:5], v[22:23] op_sel_hi:[1,0,1]
	v_add_f32_dpp v28, v28, v28 row_ror:8 row_mask:0xf bank_mask:0xf
	v_add_f32_dpp v32, v32, v32 row_ror:8 row_mask:0xf bank_mask:0xf
	v_pk_fma_f32 v[24:25], v[176:177], v[6:7], v[24:25] op_sel_hi:[1,0,1]
	v_add_f32_dpp v28, v28, v28 quad_perm:[1,0,3,2] row_mask:0xf bank_mask:0xf
	v_add_f32_dpp v32, v32, v32 quad_perm:[1,0,3,2] row_mask:0xf bank_mask:0xf
	v_pk_fma_f32 v[26:27], v[178:179], v[6:7], v[26:27] op_sel_hi:[1,0,1]
	v_add_f32_dpp v28, v28, v28 quad_perm:[2,3,0,1] row_mask:0xf bank_mask:0xf
	v_add_f32_dpp v32, v32, v32 quad_perm:[2,3,0,1] row_mask:0xf bank_mask:0xf
	ds_read_b64 v[8:9], v196 offset:1536
	ds_read_b32 v10, v36 offset:1536
	v_add_f32_e32 v39, v32, v5
	v_mov_b32_dpp v30, v28 row_half_mirror row_mask:0xf bank_mask:0xf
	v_pk_fma_f32 v[20:21], v[84:85], v[28:29], v[20:21] op_sel_hi:[1,0,1] neg_lo:[0,1,0] neg_hi:[0,1,0]
	v_pk_fma_f32 v[22:23], v[86:87], v[28:29], v[22:23] op_sel_hi:[1,0,1] neg_lo:[0,1,0] neg_hi:[0,1,0]
	v_pk_fma_f32 v[24:25], v[84:85], v[30:31], v[24:25] op_sel_hi:[1,0,1] neg_lo:[0,1,0] neg_hi:[0,1,0]
	v_pk_fma_f32 v[26:27], v[86:87], v[30:31], v[26:27] op_sel_hi:[1,0,1] neg_lo:[0,1,0] neg_hi:[0,1,0]
	ds_write_b32 v102, v39 offset:256
	ds_read_b128 v[140:143], v195 offset:1024
	ds_read_b128 v[152:155], v195 offset:9216
	ds_read_b128 v[176:179], v195 offset:17408
	ds_read_b128 v[84:87], v195 offset:33792
	ds_read_b64 v[4:5], v196 offset:2048
	ds_read_b32 v6, v36 offset:2048
	s_waitcnt lgkmcnt(7)
	v_pk_mul_f32 v[46:47], v[24:25], v[144:145] op_sel_hi:[0,1]
	v_pk_mul_f32 v[34:35], v[20:21], v[144:145] op_sel_hi:[0,1]
	v_pk_fma_f32 v[46:47], v[24:25], v[146:147], v[46:47] op_sel:[1,0,0] op_sel_hi:[1,1,1]
	v_pk_fma_f32 v[34:35], v[20:21], v[146:147], v[34:35] op_sel:[1,0,0] op_sel_hi:[1,1,1]
	v_pk_fma_f32 v[46:47], v[26:27], v[156:157], v[46:47] op_sel_hi:[0,1,1]
	v_pk_fma_f32 v[34:35], v[22:23], v[156:157], v[34:35] op_sel_hi:[0,1,1]
	v_pk_fma_f32 v[46:47], v[26:27], v[158:159], v[46:47] op_sel:[1,0,0] op_sel_hi:[1,1,1]
	v_pk_fma_f32 v[34:35], v[22:23], v[158:159], v[34:35] op_sel:[1,0,0] op_sel_hi:[1,1,1]
	v_pk_mul_f32 v[20:21], v[20:21], v[168:169]
	v_add_f32_dpp v28, v46, v34 row_half_mirror row_mask:0xf bank_mask:0xf
	v_add_f32_dpp v32, v47, v35 row_half_mirror row_mask:0xf bank_mask:0xf
	v_pk_mul_f32 v[22:23], v[22:23], v[170:171]
	v_add_f32_dpp v28, v28, v28 row_ror:8 row_mask:0xf bank_mask:0xf
	v_add_f32_dpp v32, v32, v32 row_ror:8 row_mask:0xf bank_mask:0xf
	v_pk_mul_f32 v[24:25], v[24:25], v[168:169]
	v_add_f32_dpp v28, v28, v28 quad_perm:[1,0,3,2] row_mask:0xf bank_mask:0xf
	v_add_f32_dpp v32, v32, v32 quad_perm:[1,0,3,2] row_mask:0xf bank_mask:0xf
	v_pk_mul_f32 v[26:27], v[26:27], v[170:171]
	v_add_f32_dpp v28, v28, v28 quad_perm:[2,3,0,1] row_mask:0xf bank_mask:0xf
	v_add_f32_dpp v32, v32, v32 quad_perm:[2,3,0,1] row_mask:0xf bank_mask:0xf
	v_pk_fma_f32 v[20:21], v[180:181], v[8:9], v[20:21] op_sel_hi:[1,0,1]
	v_mov_b32_dpp v30, v28 row_half_mirror row_mask:0xf bank_mask:0xf
	v_pk_fma_f32 v[22:23], v[182:183], v[8:9], v[22:23] op_sel_hi:[1,0,1]
	v_pk_fma_f32 v[24:25], v[180:181], v[10:11], v[24:25] op_sel_hi:[1,0,1]
	v_pk_fma_f32 v[26:27], v[182:183], v[10:11], v[26:27] op_sel_hi:[1,0,1]
	v_pk_fma_f32 v[20:21], v[88:89], v[28:29], v[20:21] op_sel_hi:[1,0,1] neg_lo:[0,1,0] neg_hi:[0,1,0]
	v_pk_fma_f32 v[22:23], v[90:91], v[28:29], v[22:23] op_sel_hi:[1,0,1] neg_lo:[0,1,0] neg_hi:[0,1,0]
	v_pk_fma_f32 v[24:25], v[88:89], v[30:31], v[24:25] op_sel_hi:[1,0,1] neg_lo:[0,1,0] neg_hi:[0,1,0]
	v_pk_fma_f32 v[26:27], v[90:91], v[30:31], v[26:27] op_sel_hi:[1,0,1] neg_lo:[0,1,0] neg_hi:[0,1,0]
	v_add_f32_e32 v39, v32, v9
	ds_write_b32 v102, v39 offset:384
	ds_read_b128 v[144:147], v195 offset:1280
	ds_read_b128 v[156:159], v195 offset:9472
	ds_read_b128 v[180:183], v195 offset:17664
	ds_read_b128 v[88:91], v195 offset:34048
	s_waitcnt lgkmcnt(5)
	v_pk_mul_f32 v[46:47], v[24:25], v[140:141] op_sel_hi:[0,1]
	v_pk_mul_f32 v[34:35], v[20:21], v[140:141] op_sel_hi:[0,1]
	v_pk_fma_f32 v[46:47], v[24:25], v[142:143], v[46:47] op_sel:[1,0,0] op_sel_hi:[1,1,1]
	v_pk_fma_f32 v[34:35], v[20:21], v[142:143], v[34:35] op_sel:[1,0,0] op_sel_hi:[1,1,1]
	v_pk_fma_f32 v[46:47], v[26:27], v[152:153], v[46:47] op_sel_hi:[0,1,1]
	v_pk_fma_f32 v[34:35], v[22:23], v[152:153], v[34:35] op_sel_hi:[0,1,1]
	v_pk_fma_f32 v[46:47], v[26:27], v[154:155], v[46:47] op_sel:[1,0,0] op_sel_hi:[1,1,1]
	v_pk_fma_f32 v[34:35], v[22:23], v[154:155], v[34:35] op_sel:[1,0,0] op_sel_hi:[1,1,1]
	v_pk_fma_f32 v[20:21], v[176:177], v[4:5], v[20:21] op_sel_hi:[1,0,1]
	v_add_f32_dpp v28, v46, v34 row_half_mirror row_mask:0xf bank_mask:0xf
	v_add_f32_dpp v32, v47, v35 row_half_mirror row_mask:0xf bank_mask:0xf
	v_pk_fma_f32 v[22:23], v[178:179], v[4:5], v[22:23] op_sel_hi:[1,0,1]
	v_add_f32_dpp v28, v28, v28 row_ror:8 row_mask:0xf bank_mask:0xf
	v_add_f32_dpp v32, v32, v32 row_ror:8 row_mask:0xf bank_mask:0xf
	v_pk_fma_f32 v[24:25], v[176:177], v[6:7], v[24:25] op_sel_hi:[1,0,1]
	v_add_f32_dpp v28, v28, v28 quad_perm:[1,0,3,2] row_mask:0xf bank_mask:0xf
	v_add_f32_dpp v32, v32, v32 quad_perm:[1,0,3,2] row_mask:0xf bank_mask:0xf
	v_pk_fma_f32 v[26:27], v[178:179], v[6:7], v[26:27] op_sel_hi:[1,0,1]
	v_add_f32_dpp v28, v28, v28 quad_perm:[2,3,0,1] row_mask:0xf bank_mask:0xf
	v_add_f32_dpp v32, v32, v32 quad_perm:[2,3,0,1] row_mask:0xf bank_mask:0xf
	ds_read_b64 v[8:9], v196 offset:2560
	ds_read_b32 v10, v36 offset:2560
	v_add_f32_e32 v39, v32, v5
	v_mov_b32_dpp v30, v28 row_half_mirror row_mask:0xf bank_mask:0xf
	v_pk_fma_f32 v[20:21], v[84:85], v[28:29], v[20:21] op_sel_hi:[1,0,1] neg_lo:[0,1,0] neg_hi:[0,1,0]
	v_pk_fma_f32 v[22:23], v[86:87], v[28:29], v[22:23] op_sel_hi:[1,0,1] neg_lo:[0,1,0] neg_hi:[0,1,0]
	v_pk_fma_f32 v[24:25], v[84:85], v[30:31], v[24:25] op_sel_hi:[1,0,1] neg_lo:[0,1,0] neg_hi:[0,1,0]
	v_pk_fma_f32 v[26:27], v[86:87], v[30:31], v[26:27] op_sel_hi:[1,0,1] neg_lo:[0,1,0] neg_hi:[0,1,0]
	ds_write_b32 v102, v39 offset:512
	ds_read_b128 v[140:143], v195 offset:1536
	ds_read_b128 v[152:155], v195 offset:9728
	ds_read_b128 v[176:179], v195 offset:17920
	ds_read_b128 v[84:87], v195 offset:34304
	s_waitcnt lgkmcnt(5)
	v_pk_mul_f32 v[46:47], v[24:25], v[144:145] op_sel_hi:[0,1]
	v_pk_mul_f32 v[34:35], v[20:21], v[144:145] op_sel_hi:[0,1]
	v_pk_fma_f32 v[46:47], v[24:25], v[146:147], v[46:47] op_sel:[1,0,0] op_sel_hi:[1,1,1]
	v_pk_fma_f32 v[34:35], v[20:21], v[146:147], v[34:35] op_sel:[1,0,0] op_sel_hi:[1,1,1]
	v_pk_fma_f32 v[46:47], v[26:27], v[156:157], v[46:47] op_sel_hi:[0,1,1]
	v_pk_fma_f32 v[34:35], v[22:23], v[156:157], v[34:35] op_sel_hi:[0,1,1]
	v_pk_fma_f32 v[46:47], v[26:27], v[158:159], v[46:47] op_sel:[1,0,0] op_sel_hi:[1,1,1]
	v_pk_fma_f32 v[34:35], v[22:23], v[158:159], v[34:35] op_sel:[1,0,0] op_sel_hi:[1,1,1]
	v_pk_fma_f32 v[20:21], v[180:181], v[8:9], v[20:21] op_sel_hi:[1,0,1]
	v_add_f32_dpp v28, v46, v34 row_half_mirror row_mask:0xf bank_mask:0xf
	v_add_f32_dpp v32, v47, v35 row_half_mirror row_mask:0xf bank_mask:0xf
	v_pk_fma_f32 v[22:23], v[182:183], v[8:9], v[22:23] op_sel_hi:[1,0,1]
	v_add_f32_dpp v28, v28, v28 row_ror:8 row_mask:0xf bank_mask:0xf
	v_add_f32_dpp v32, v32, v32 row_ror:8 row_mask:0xf bank_mask:0xf
	v_pk_fma_f32 v[24:25], v[180:181], v[10:11], v[24:25] op_sel_hi:[1,0,1]
	v_add_f32_dpp v28, v28, v28 quad_perm:[1,0,3,2] row_mask:0xf bank_mask:0xf
	v_add_f32_dpp v32, v32, v32 quad_perm:[1,0,3,2] row_mask:0xf bank_mask:0xf
	v_pk_fma_f32 v[26:27], v[182:183], v[10:11], v[26:27] op_sel_hi:[1,0,1]
	v_add_f32_dpp v28, v28, v28 quad_perm:[2,3,0,1] row_mask:0xf bank_mask:0xf
	v_add_f32_dpp v32, v32, v32 quad_perm:[2,3,0,1] row_mask:0xf bank_mask:0xf
	ds_read_b64 v[4:5], v196 offset:3072
	ds_read_b32 v6, v36 offset:3072
	v_add_f32_e32 v39, v32, v9
	v_mov_b32_dpp v30, v28 row_half_mirror row_mask:0xf bank_mask:0xf
	v_pk_fma_f32 v[20:21], v[88:89], v[28:29], v[20:21] op_sel_hi:[1,0,1] neg_lo:[0,1,0] neg_hi:[0,1,0]
	v_pk_fma_f32 v[22:23], v[90:91], v[28:29], v[22:23] op_sel_hi:[1,0,1] neg_lo:[0,1,0] neg_hi:[0,1,0]
	v_pk_fma_f32 v[24:25], v[88:89], v[30:31], v[24:25] op_sel_hi:[1,0,1] neg_lo:[0,1,0] neg_hi:[0,1,0]
	v_pk_fma_f32 v[26:27], v[90:91], v[30:31], v[26:27] op_sel_hi:[1,0,1] neg_lo:[0,1,0] neg_hi:[0,1,0]
	ds_write_b32 v102, v39 offset:640
	ds_read_b128 v[144:147], v195 offset:1792
	ds_read_b128 v[156:159], v195 offset:9984
	ds_read_b128 v[168:171], v195 offset:26368
	ds_read_b128 v[180:183], v195 offset:18176
	ds_read_b128 v[88:91], v195 offset:34560
	s_waitcnt lgkmcnt(6)
	v_pk_mul_f32 v[46:47], v[24:25], v[140:141] op_sel_hi:[0,1]
	v_pk_mul_f32 v[34:35], v[20:21], v[140:141] op_sel_hi:[0,1]
	v_pk_fma_f32 v[46:47], v[24:25], v[142:143], v[46:47] op_sel:[1,0,0] op_sel_hi:[1,1,1]
	v_pk_fma_f32 v[34:35], v[20:21], v[142:143], v[34:35] op_sel:[1,0,0] op_sel_hi:[1,1,1]
	v_pk_fma_f32 v[46:47], v[26:27], v[152:153], v[46:47] op_sel_hi:[0,1,1]
	v_pk_fma_f32 v[34:35], v[22:23], v[152:153], v[34:35] op_sel_hi:[0,1,1]
	v_pk_fma_f32 v[46:47], v[26:27], v[154:155], v[46:47] op_sel:[1,0,0] op_sel_hi:[1,1,1]
	v_pk_fma_f32 v[34:35], v[22:23], v[154:155], v[34:35] op_sel:[1,0,0] op_sel_hi:[1,1,1]
	v_pk_fma_f32 v[20:21], v[176:177], v[4:5], v[20:21] op_sel_hi:[1,0,1]
	v_add_f32_dpp v28, v46, v34 row_half_mirror row_mask:0xf bank_mask:0xf
	v_add_f32_dpp v32, v47, v35 row_half_mirror row_mask:0xf bank_mask:0xf
	v_pk_fma_f32 v[22:23], v[178:179], v[4:5], v[22:23] op_sel_hi:[1,0,1]
	v_add_f32_dpp v28, v28, v28 row_ror:8 row_mask:0xf bank_mask:0xf
	v_add_f32_dpp v32, v32, v32 row_ror:8 row_mask:0xf bank_mask:0xf
	v_pk_fma_f32 v[24:25], v[176:177], v[6:7], v[24:25] op_sel_hi:[1,0,1]
	v_add_f32_dpp v28, v28, v28 quad_perm:[1,0,3,2] row_mask:0xf bank_mask:0xf
	v_add_f32_dpp v32, v32, v32 quad_perm:[1,0,3,2] row_mask:0xf bank_mask:0xf
	v_pk_fma_f32 v[26:27], v[178:179], v[6:7], v[26:27] op_sel_hi:[1,0,1]
	v_add_f32_dpp v28, v28, v28 quad_perm:[2,3,0,1] row_mask:0xf bank_mask:0xf
	v_add_f32_dpp v32, v32, v32 quad_perm:[2,3,0,1] row_mask:0xf bank_mask:0xf
	ds_read_b64 v[8:9], v196 offset:3584
	ds_read_b32 v10, v36 offset:3584
	v_add_f32_e32 v39, v32, v5
	v_mov_b32_dpp v30, v28 row_half_mirror row_mask:0xf bank_mask:0xf
	v_pk_fma_f32 v[20:21], v[84:85], v[28:29], v[20:21] op_sel_hi:[1,0,1] neg_lo:[0,1,0] neg_hi:[0,1,0]
	v_pk_fma_f32 v[22:23], v[86:87], v[28:29], v[22:23] op_sel_hi:[1,0,1] neg_lo:[0,1,0] neg_hi:[0,1,0]
	v_pk_fma_f32 v[24:25], v[84:85], v[30:31], v[24:25] op_sel_hi:[1,0,1] neg_lo:[0,1,0] neg_hi:[0,1,0]
	v_pk_fma_f32 v[26:27], v[86:87], v[30:31], v[26:27] op_sel_hi:[1,0,1] neg_lo:[0,1,0] neg_hi:[0,1,0]
	ds_write_b32 v102, v39 offset:768
	ds_read_b128 v[140:143], v195 offset:2048
	ds_read_b128 v[152:155], v195 offset:10240
	ds_read_b128 v[176:179], v195 offset:18432
	ds_read_b128 v[84:87], v195 offset:34816
	ds_read_b64 v[4:5], v196 offset:4096
	ds_read_b32 v6, v36 offset:4096
	s_waitcnt lgkmcnt(7)
	v_pk_mul_f32 v[46:47], v[24:25], v[144:145] op_sel_hi:[0,1]
	v_pk_mul_f32 v[34:35], v[20:21], v[144:145] op_sel_hi:[0,1]
	v_pk_fma_f32 v[46:47], v[24:25], v[146:147], v[46:47] op_sel:[1,0,0] op_sel_hi:[1,1,1]
	v_pk_fma_f32 v[34:35], v[20:21], v[146:147], v[34:35] op_sel:[1,0,0] op_sel_hi:[1,1,1]
	v_pk_fma_f32 v[46:47], v[26:27], v[156:157], v[46:47] op_sel_hi:[0,1,1]
	v_pk_fma_f32 v[34:35], v[22:23], v[156:157], v[34:35] op_sel_hi:[0,1,1]
	v_pk_fma_f32 v[46:47], v[26:27], v[158:159], v[46:47] op_sel:[1,0,0] op_sel_hi:[1,1,1]
	v_pk_fma_f32 v[34:35], v[22:23], v[158:159], v[34:35] op_sel:[1,0,0] op_sel_hi:[1,1,1]
	v_pk_mul_f32 v[20:21], v[20:21], v[168:169]
	v_add_f32_dpp v28, v46, v34 row_half_mirror row_mask:0xf bank_mask:0xf
	v_add_f32_dpp v32, v47, v35 row_half_mirror row_mask:0xf bank_mask:0xf
	v_pk_mul_f32 v[22:23], v[22:23], v[170:171]
	v_add_f32_dpp v28, v28, v28 row_ror:8 row_mask:0xf bank_mask:0xf
	v_add_f32_dpp v32, v32, v32 row_ror:8 row_mask:0xf bank_mask:0xf
	v_pk_mul_f32 v[24:25], v[24:25], v[168:169]
	v_add_f32_dpp v28, v28, v28 quad_perm:[1,0,3,2] row_mask:0xf bank_mask:0xf
	v_add_f32_dpp v32, v32, v32 quad_perm:[1,0,3,2] row_mask:0xf bank_mask:0xf
	v_pk_mul_f32 v[26:27], v[26:27], v[170:171]
	v_add_f32_dpp v28, v28, v28 quad_perm:[2,3,0,1] row_mask:0xf bank_mask:0xf
	v_add_f32_dpp v32, v32, v32 quad_perm:[2,3,0,1] row_mask:0xf bank_mask:0xf
	v_pk_fma_f32 v[20:21], v[180:181], v[8:9], v[20:21] op_sel_hi:[1,0,1]
	v_mov_b32_dpp v30, v28 row_half_mirror row_mask:0xf bank_mask:0xf
	v_pk_fma_f32 v[22:23], v[182:183], v[8:9], v[22:23] op_sel_hi:[1,0,1]
	v_pk_fma_f32 v[24:25], v[180:181], v[10:11], v[24:25] op_sel_hi:[1,0,1]
	v_pk_fma_f32 v[26:27], v[182:183], v[10:11], v[26:27] op_sel_hi:[1,0,1]
	v_pk_fma_f32 v[20:21], v[88:89], v[28:29], v[20:21] op_sel_hi:[1,0,1] neg_lo:[0,1,0] neg_hi:[0,1,0]
	v_pk_fma_f32 v[22:23], v[90:91], v[28:29], v[22:23] op_sel_hi:[1,0,1] neg_lo:[0,1,0] neg_hi:[0,1,0]
	v_pk_fma_f32 v[24:25], v[88:89], v[30:31], v[24:25] op_sel_hi:[1,0,1] neg_lo:[0,1,0] neg_hi:[0,1,0]
	v_pk_fma_f32 v[26:27], v[90:91], v[30:31], v[26:27] op_sel_hi:[1,0,1] neg_lo:[0,1,0] neg_hi:[0,1,0]
	v_add_f32_e32 v39, v32, v9
	ds_write_b32 v102, v39 offset:896
	ds_read_b128 v[144:147], v195 offset:2304
	ds_read_b128 v[156:159], v195 offset:10496
	ds_read_b128 v[180:183], v195 offset:18688
	ds_read_b128 v[88:91], v195 offset:35072
	s_waitcnt lgkmcnt(5)
	v_pk_mul_f32 v[46:47], v[24:25], v[140:141] op_sel_hi:[0,1]
	v_pk_mul_f32 v[34:35], v[20:21], v[140:141] op_sel_hi:[0,1]
	v_pk_fma_f32 v[46:47], v[24:25], v[142:143], v[46:47] op_sel:[1,0,0] op_sel_hi:[1,1,1]
	v_pk_fma_f32 v[34:35], v[20:21], v[142:143], v[34:35] op_sel:[1,0,0] op_sel_hi:[1,1,1]
	v_pk_fma_f32 v[46:47], v[26:27], v[152:153], v[46:47] op_sel_hi:[0,1,1]
	v_pk_fma_f32 v[34:35], v[22:23], v[152:153], v[34:35] op_sel_hi:[0,1,1]
	v_pk_fma_f32 v[46:47], v[26:27], v[154:155], v[46:47] op_sel:[1,0,0] op_sel_hi:[1,1,1]
	v_pk_fma_f32 v[34:35], v[22:23], v[154:155], v[34:35] op_sel:[1,0,0] op_sel_hi:[1,1,1]
	v_pk_fma_f32 v[20:21], v[176:177], v[4:5], v[20:21] op_sel_hi:[1,0,1]
	v_add_f32_dpp v28, v46, v34 row_half_mirror row_mask:0xf bank_mask:0xf
	v_add_f32_dpp v32, v47, v35 row_half_mirror row_mask:0xf bank_mask:0xf
	v_pk_fma_f32 v[22:23], v[178:179], v[4:5], v[22:23] op_sel_hi:[1,0,1]
	v_add_f32_dpp v28, v28, v28 row_ror:8 row_mask:0xf bank_mask:0xf
	v_add_f32_dpp v32, v32, v32 row_ror:8 row_mask:0xf bank_mask:0xf
	v_pk_fma_f32 v[24:25], v[176:177], v[6:7], v[24:25] op_sel_hi:[1,0,1]
	v_add_f32_dpp v28, v28, v28 quad_perm:[1,0,3,2] row_mask:0xf bank_mask:0xf
	v_add_f32_dpp v32, v32, v32 quad_perm:[1,0,3,2] row_mask:0xf bank_mask:0xf
	v_pk_fma_f32 v[26:27], v[178:179], v[6:7], v[26:27] op_sel_hi:[1,0,1]
	v_add_f32_dpp v28, v28, v28 quad_perm:[2,3,0,1] row_mask:0xf bank_mask:0xf
	v_add_f32_dpp v32, v32, v32 quad_perm:[2,3,0,1] row_mask:0xf bank_mask:0xf
	ds_read_b64 v[8:9], v196 offset:4608
	ds_read_b32 v10, v36 offset:4608
	v_add_f32_e32 v39, v32, v5
	v_mov_b32_dpp v30, v28 row_half_mirror row_mask:0xf bank_mask:0xf
	v_pk_fma_f32 v[20:21], v[84:85], v[28:29], v[20:21] op_sel_hi:[1,0,1] neg_lo:[0,1,0] neg_hi:[0,1,0]
	v_pk_fma_f32 v[22:23], v[86:87], v[28:29], v[22:23] op_sel_hi:[1,0,1] neg_lo:[0,1,0] neg_hi:[0,1,0]
	v_pk_fma_f32 v[24:25], v[84:85], v[30:31], v[24:25] op_sel_hi:[1,0,1] neg_lo:[0,1,0] neg_hi:[0,1,0]
	v_pk_fma_f32 v[26:27], v[86:87], v[30:31], v[26:27] op_sel_hi:[1,0,1] neg_lo:[0,1,0] neg_hi:[0,1,0]
	ds_write_b32 v102, v39 offset:1024
	ds_read_b128 v[140:143], v195 offset:2560
	ds_read_b128 v[152:155], v195 offset:10752
	ds_read_b128 v[176:179], v195 offset:18944
	ds_read_b128 v[84:87], v195 offset:35328
	s_waitcnt lgkmcnt(5)
	v_pk_mul_f32 v[46:47], v[24:25], v[144:145] op_sel_hi:[0,1]
	v_pk_mul_f32 v[34:35], v[20:21], v[144:145] op_sel_hi:[0,1]
	v_pk_fma_f32 v[46:47], v[24:25], v[146:147], v[46:47] op_sel:[1,0,0] op_sel_hi:[1,1,1]
	v_pk_fma_f32 v[34:35], v[20:21], v[146:147], v[34:35] op_sel:[1,0,0] op_sel_hi:[1,1,1]
	v_pk_fma_f32 v[46:47], v[26:27], v[156:157], v[46:47] op_sel_hi:[0,1,1]
	v_pk_fma_f32 v[34:35], v[22:23], v[156:157], v[34:35] op_sel_hi:[0,1,1]
	v_pk_fma_f32 v[46:47], v[26:27], v[158:159], v[46:47] op_sel:[1,0,0] op_sel_hi:[1,1,1]
	v_pk_fma_f32 v[34:35], v[22:23], v[158:159], v[34:35] op_sel:[1,0,0] op_sel_hi:[1,1,1]
	v_pk_fma_f32 v[20:21], v[180:181], v[8:9], v[20:21] op_sel_hi:[1,0,1]
	v_add_f32_dpp v28, v46, v34 row_half_mirror row_mask:0xf bank_mask:0xf
	v_add_f32_dpp v32, v47, v35 row_half_mirror row_mask:0xf bank_mask:0xf
	v_pk_fma_f32 v[22:23], v[182:183], v[8:9], v[22:23] op_sel_hi:[1,0,1]
	v_add_f32_dpp v28, v28, v28 row_ror:8 row_mask:0xf bank_mask:0xf
	v_add_f32_dpp v32, v32, v32 row_ror:8 row_mask:0xf bank_mask:0xf
	v_pk_fma_f32 v[24:25], v[180:181], v[10:11], v[24:25] op_sel_hi:[1,0,1]
	v_add_f32_dpp v28, v28, v28 quad_perm:[1,0,3,2] row_mask:0xf bank_mask:0xf
	v_add_f32_dpp v32, v32, v32 quad_perm:[1,0,3,2] row_mask:0xf bank_mask:0xf
	v_pk_fma_f32 v[26:27], v[182:183], v[10:11], v[26:27] op_sel_hi:[1,0,1]
	v_add_f32_dpp v28, v28, v28 quad_perm:[2,3,0,1] row_mask:0xf bank_mask:0xf
	v_add_f32_dpp v32, v32, v32 quad_perm:[2,3,0,1] row_mask:0xf bank_mask:0xf
	ds_read_b64 v[4:5], v196 offset:5120
	ds_read_b32 v6, v36 offset:5120
	v_add_f32_e32 v39, v32, v9
	v_mov_b32_dpp v30, v28 row_half_mirror row_mask:0xf bank_mask:0xf
	v_pk_fma_f32 v[20:21], v[88:89], v[28:29], v[20:21] op_sel_hi:[1,0,1] neg_lo:[0,1,0] neg_hi:[0,1,0]
	v_pk_fma_f32 v[22:23], v[90:91], v[28:29], v[22:23] op_sel_hi:[1,0,1] neg_lo:[0,1,0] neg_hi:[0,1,0]
	v_pk_fma_f32 v[24:25], v[88:89], v[30:31], v[24:25] op_sel_hi:[1,0,1] neg_lo:[0,1,0] neg_hi:[0,1,0]
	v_pk_fma_f32 v[26:27], v[90:91], v[30:31], v[26:27] op_sel_hi:[1,0,1] neg_lo:[0,1,0] neg_hi:[0,1,0]
	ds_write_b32 v102, v39 offset:1152
	ds_read_b128 v[144:147], v195 offset:2816
	ds_read_b128 v[156:159], v195 offset:11008
	ds_read_b128 v[168:171], v195 offset:27392
	ds_read_b128 v[180:183], v195 offset:19200
	ds_read_b128 v[88:91], v195 offset:35584
	s_waitcnt lgkmcnt(6)
	v_pk_mul_f32 v[46:47], v[24:25], v[140:141] op_sel_hi:[0,1]
	v_pk_mul_f32 v[34:35], v[20:21], v[140:141] op_sel_hi:[0,1]
	v_pk_fma_f32 v[46:47], v[24:25], v[142:143], v[46:47] op_sel:[1,0,0] op_sel_hi:[1,1,1]
	v_pk_fma_f32 v[34:35], v[20:21], v[142:143], v[34:35] op_sel:[1,0,0] op_sel_hi:[1,1,1]
	v_pk_fma_f32 v[46:47], v[26:27], v[152:153], v[46:47] op_sel_hi:[0,1,1]
	v_pk_fma_f32 v[34:35], v[22:23], v[152:153], v[34:35] op_sel_hi:[0,1,1]
	v_pk_fma_f32 v[46:47], v[26:27], v[154:155], v[46:47] op_sel:[1,0,0] op_sel_hi:[1,1,1]
	v_pk_fma_f32 v[34:35], v[22:23], v[154:155], v[34:35] op_sel:[1,0,0] op_sel_hi:[1,1,1]
	v_pk_fma_f32 v[20:21], v[176:177], v[4:5], v[20:21] op_sel_hi:[1,0,1]
	v_add_f32_dpp v28, v46, v34 row_half_mirror row_mask:0xf bank_mask:0xf
	v_add_f32_dpp v32, v47, v35 row_half_mirror row_mask:0xf bank_mask:0xf
	v_pk_fma_f32 v[22:23], v[178:179], v[4:5], v[22:23] op_sel_hi:[1,0,1]
	v_add_f32_dpp v28, v28, v28 row_ror:8 row_mask:0xf bank_mask:0xf
	v_add_f32_dpp v32, v32, v32 row_ror:8 row_mask:0xf bank_mask:0xf
	v_pk_fma_f32 v[24:25], v[176:177], v[6:7], v[24:25] op_sel_hi:[1,0,1]
	v_add_f32_dpp v28, v28, v28 quad_perm:[1,0,3,2] row_mask:0xf bank_mask:0xf
	v_add_f32_dpp v32, v32, v32 quad_perm:[1,0,3,2] row_mask:0xf bank_mask:0xf
	v_pk_fma_f32 v[26:27], v[178:179], v[6:7], v[26:27] op_sel_hi:[1,0,1]
	v_add_f32_dpp v28, v28, v28 quad_perm:[2,3,0,1] row_mask:0xf bank_mask:0xf
	v_add_f32_dpp v32, v32, v32 quad_perm:[2,3,0,1] row_mask:0xf bank_mask:0xf
	ds_read_b64 v[8:9], v196 offset:5632
	ds_read_b32 v10, v36 offset:5632
	v_add_f32_e32 v39, v32, v5
	v_mov_b32_dpp v30, v28 row_half_mirror row_mask:0xf bank_mask:0xf
	v_pk_fma_f32 v[20:21], v[84:85], v[28:29], v[20:21] op_sel_hi:[1,0,1] neg_lo:[0,1,0] neg_hi:[0,1,0]
	v_pk_fma_f32 v[22:23], v[86:87], v[28:29], v[22:23] op_sel_hi:[1,0,1] neg_lo:[0,1,0] neg_hi:[0,1,0]
	v_pk_fma_f32 v[24:25], v[84:85], v[30:31], v[24:25] op_sel_hi:[1,0,1] neg_lo:[0,1,0] neg_hi:[0,1,0]
	v_pk_fma_f32 v[26:27], v[86:87], v[30:31], v[26:27] op_sel_hi:[1,0,1] neg_lo:[0,1,0] neg_hi:[0,1,0]
	ds_write_b32 v102, v39 offset:1280
	ds_read_b128 v[140:143], v195 offset:3072
	ds_read_b128 v[152:155], v195 offset:11264
	ds_read_b128 v[176:179], v195 offset:19456
	ds_read_b128 v[84:87], v195 offset:35840
	ds_read_b64 v[4:5], v196 offset:6144
	ds_read_b32 v6, v36 offset:6144
	s_waitcnt lgkmcnt(7)
	v_pk_mul_f32 v[46:47], v[24:25], v[144:145] op_sel_hi:[0,1]
	v_pk_mul_f32 v[34:35], v[20:21], v[144:145] op_sel_hi:[0,1]
	v_pk_fma_f32 v[46:47], v[24:25], v[146:147], v[46:47] op_sel:[1,0,0] op_sel_hi:[1,1,1]
	v_pk_fma_f32 v[34:35], v[20:21], v[146:147], v[34:35] op_sel:[1,0,0] op_sel_hi:[1,1,1]
	v_pk_fma_f32 v[46:47], v[26:27], v[156:157], v[46:47] op_sel_hi:[0,1,1]
	v_pk_fma_f32 v[34:35], v[22:23], v[156:157], v[34:35] op_sel_hi:[0,1,1]
	v_pk_fma_f32 v[46:47], v[26:27], v[158:159], v[46:47] op_sel:[1,0,0] op_sel_hi:[1,1,1]
	v_pk_fma_f32 v[34:35], v[22:23], v[158:159], v[34:35] op_sel:[1,0,0] op_sel_hi:[1,1,1]
	v_pk_mul_f32 v[20:21], v[20:21], v[168:169]
	v_add_f32_dpp v28, v46, v34 row_half_mirror row_mask:0xf bank_mask:0xf
	v_add_f32_dpp v32, v47, v35 row_half_mirror row_mask:0xf bank_mask:0xf
	v_pk_mul_f32 v[22:23], v[22:23], v[170:171]
	v_add_f32_dpp v28, v28, v28 row_ror:8 row_mask:0xf bank_mask:0xf
	v_add_f32_dpp v32, v32, v32 row_ror:8 row_mask:0xf bank_mask:0xf
	v_pk_mul_f32 v[24:25], v[24:25], v[168:169]
	v_add_f32_dpp v28, v28, v28 quad_perm:[1,0,3,2] row_mask:0xf bank_mask:0xf
	v_add_f32_dpp v32, v32, v32 quad_perm:[1,0,3,2] row_mask:0xf bank_mask:0xf
	v_pk_mul_f32 v[26:27], v[26:27], v[170:171]
	v_add_f32_dpp v28, v28, v28 quad_perm:[2,3,0,1] row_mask:0xf bank_mask:0xf
	v_add_f32_dpp v32, v32, v32 quad_perm:[2,3,0,1] row_mask:0xf bank_mask:0xf
	v_pk_fma_f32 v[20:21], v[180:181], v[8:9], v[20:21] op_sel_hi:[1,0,1]
	v_mov_b32_dpp v30, v28 row_half_mirror row_mask:0xf bank_mask:0xf
	v_pk_fma_f32 v[22:23], v[182:183], v[8:9], v[22:23] op_sel_hi:[1,0,1]
	v_pk_fma_f32 v[24:25], v[180:181], v[10:11], v[24:25] op_sel_hi:[1,0,1]
	v_pk_fma_f32 v[26:27], v[182:183], v[10:11], v[26:27] op_sel_hi:[1,0,1]
	v_pk_fma_f32 v[20:21], v[88:89], v[28:29], v[20:21] op_sel_hi:[1,0,1] neg_lo:[0,1,0] neg_hi:[0,1,0]
	v_pk_fma_f32 v[22:23], v[90:91], v[28:29], v[22:23] op_sel_hi:[1,0,1] neg_lo:[0,1,0] neg_hi:[0,1,0]
	v_pk_fma_f32 v[24:25], v[88:89], v[30:31], v[24:25] op_sel_hi:[1,0,1] neg_lo:[0,1,0] neg_hi:[0,1,0]
	v_pk_fma_f32 v[26:27], v[90:91], v[30:31], v[26:27] op_sel_hi:[1,0,1] neg_lo:[0,1,0] neg_hi:[0,1,0]
	v_add_f32_e32 v39, v32, v9
	ds_write_b32 v102, v39 offset:1408
	ds_read_b128 v[144:147], v195 offset:3328
	ds_read_b128 v[156:159], v195 offset:11520
	ds_read_b128 v[180:183], v195 offset:19712
	ds_read_b128 v[88:91], v195 offset:36096
	s_waitcnt lgkmcnt(5)
	v_pk_mul_f32 v[46:47], v[24:25], v[140:141] op_sel_hi:[0,1]
	v_pk_mul_f32 v[34:35], v[20:21], v[140:141] op_sel_hi:[0,1]
	v_pk_fma_f32 v[46:47], v[24:25], v[142:143], v[46:47] op_sel:[1,0,0] op_sel_hi:[1,1,1]
	v_pk_fma_f32 v[34:35], v[20:21], v[142:143], v[34:35] op_sel:[1,0,0] op_sel_hi:[1,1,1]
	v_pk_fma_f32 v[46:47], v[26:27], v[152:153], v[46:47] op_sel_hi:[0,1,1]
	v_pk_fma_f32 v[34:35], v[22:23], v[152:153], v[34:35] op_sel_hi:[0,1,1]
	v_pk_fma_f32 v[46:47], v[26:27], v[154:155], v[46:47] op_sel:[1,0,0] op_sel_hi:[1,1,1]
	v_pk_fma_f32 v[34:35], v[22:23], v[154:155], v[34:35] op_sel:[1,0,0] op_sel_hi:[1,1,1]
	v_pk_fma_f32 v[20:21], v[176:177], v[4:5], v[20:21] op_sel_hi:[1,0,1]
	v_add_f32_dpp v28, v46, v34 row_half_mirror row_mask:0xf bank_mask:0xf
	v_add_f32_dpp v32, v47, v35 row_half_mirror row_mask:0xf bank_mask:0xf
	v_pk_fma_f32 v[22:23], v[178:179], v[4:5], v[22:23] op_sel_hi:[1,0,1]
	v_add_f32_dpp v28, v28, v28 row_ror:8 row_mask:0xf bank_mask:0xf
	v_add_f32_dpp v32, v32, v32 row_ror:8 row_mask:0xf bank_mask:0xf
	v_pk_fma_f32 v[24:25], v[176:177], v[6:7], v[24:25] op_sel_hi:[1,0,1]
	v_add_f32_dpp v28, v28, v28 quad_perm:[1,0,3,2] row_mask:0xf bank_mask:0xf
	v_add_f32_dpp v32, v32, v32 quad_perm:[1,0,3,2] row_mask:0xf bank_mask:0xf
	v_pk_fma_f32 v[26:27], v[178:179], v[6:7], v[26:27] op_sel_hi:[1,0,1]
	v_add_f32_dpp v28, v28, v28 quad_perm:[2,3,0,1] row_mask:0xf bank_mask:0xf
	v_add_f32_dpp v32, v32, v32 quad_perm:[2,3,0,1] row_mask:0xf bank_mask:0xf
	ds_read_b64 v[8:9], v196 offset:6656
	ds_read_b32 v10, v36 offset:6656
	v_add_f32_e32 v39, v32, v5
	v_mov_b32_dpp v30, v28 row_half_mirror row_mask:0xf bank_mask:0xf
	v_pk_fma_f32 v[20:21], v[84:85], v[28:29], v[20:21] op_sel_hi:[1,0,1] neg_lo:[0,1,0] neg_hi:[0,1,0]
	v_pk_fma_f32 v[22:23], v[86:87], v[28:29], v[22:23] op_sel_hi:[1,0,1] neg_lo:[0,1,0] neg_hi:[0,1,0]
	v_pk_fma_f32 v[24:25], v[84:85], v[30:31], v[24:25] op_sel_hi:[1,0,1] neg_lo:[0,1,0] neg_hi:[0,1,0]
	v_pk_fma_f32 v[26:27], v[86:87], v[30:31], v[26:27] op_sel_hi:[1,0,1] neg_lo:[0,1,0] neg_hi:[0,1,0]
	ds_write_b32 v102, v39 offset:1536
	ds_read_b128 v[140:143], v195 offset:3584
	ds_read_b128 v[152:155], v195 offset:11776
	ds_read_b128 v[176:179], v195 offset:19968
	ds_read_b128 v[84:87], v195 offset:36352
	s_waitcnt lgkmcnt(5)
	v_pk_mul_f32 v[46:47], v[24:25], v[144:145] op_sel_hi:[0,1]
	v_pk_mul_f32 v[34:35], v[20:21], v[144:145] op_sel_hi:[0,1]
	v_pk_fma_f32 v[46:47], v[24:25], v[146:147], v[46:47] op_sel:[1,0,0] op_sel_hi:[1,1,1]
	v_pk_fma_f32 v[34:35], v[20:21], v[146:147], v[34:35] op_sel:[1,0,0] op_sel_hi:[1,1,1]
	v_pk_fma_f32 v[46:47], v[26:27], v[156:157], v[46:47] op_sel_hi:[0,1,1]
	v_pk_fma_f32 v[34:35], v[22:23], v[156:157], v[34:35] op_sel_hi:[0,1,1]
	v_pk_fma_f32 v[46:47], v[26:27], v[158:159], v[46:47] op_sel:[1,0,0] op_sel_hi:[1,1,1]
	v_pk_fma_f32 v[34:35], v[22:23], v[158:159], v[34:35] op_sel:[1,0,0] op_sel_hi:[1,1,1]
	v_pk_fma_f32 v[20:21], v[180:181], v[8:9], v[20:21] op_sel_hi:[1,0,1]
	v_add_f32_dpp v28, v46, v34 row_half_mirror row_mask:0xf bank_mask:0xf
	v_add_f32_dpp v32, v47, v35 row_half_mirror row_mask:0xf bank_mask:0xf
	v_pk_fma_f32 v[22:23], v[182:183], v[8:9], v[22:23] op_sel_hi:[1,0,1]
	v_add_f32_dpp v28, v28, v28 row_ror:8 row_mask:0xf bank_mask:0xf
	v_add_f32_dpp v32, v32, v32 row_ror:8 row_mask:0xf bank_mask:0xf
	v_pk_fma_f32 v[24:25], v[180:181], v[10:11], v[24:25] op_sel_hi:[1,0,1]
	v_add_f32_dpp v28, v28, v28 quad_perm:[1,0,3,2] row_mask:0xf bank_mask:0xf
	v_add_f32_dpp v32, v32, v32 quad_perm:[1,0,3,2] row_mask:0xf bank_mask:0xf
	v_pk_fma_f32 v[26:27], v[182:183], v[10:11], v[26:27] op_sel_hi:[1,0,1]
	v_add_f32_dpp v28, v28, v28 quad_perm:[2,3,0,1] row_mask:0xf bank_mask:0xf
	v_add_f32_dpp v32, v32, v32 quad_perm:[2,3,0,1] row_mask:0xf bank_mask:0xf
	ds_read_b64 v[4:5], v196 offset:7168
	ds_read_b32 v6, v36 offset:7168
	v_add_f32_e32 v39, v32, v9
	v_mov_b32_dpp v30, v28 row_half_mirror row_mask:0xf bank_mask:0xf
	v_pk_fma_f32 v[20:21], v[88:89], v[28:29], v[20:21] op_sel_hi:[1,0,1] neg_lo:[0,1,0] neg_hi:[0,1,0]
	v_pk_fma_f32 v[22:23], v[90:91], v[28:29], v[22:23] op_sel_hi:[1,0,1] neg_lo:[0,1,0] neg_hi:[0,1,0]
	v_pk_fma_f32 v[24:25], v[88:89], v[30:31], v[24:25] op_sel_hi:[1,0,1] neg_lo:[0,1,0] neg_hi:[0,1,0]
	v_pk_fma_f32 v[26:27], v[90:91], v[30:31], v[26:27] op_sel_hi:[1,0,1] neg_lo:[0,1,0] neg_hi:[0,1,0]
	ds_write_b32 v102, v39 offset:1664
	ds_read_b128 v[144:147], v195 offset:3840
	ds_read_b128 v[156:159], v195 offset:12032
	ds_read_b128 v[168:171], v195 offset:28416
	ds_read_b128 v[180:183], v195 offset:20224
	ds_read_b128 v[88:91], v195 offset:36608
	s_waitcnt lgkmcnt(6)
	v_pk_mul_f32 v[46:47], v[24:25], v[140:141] op_sel_hi:[0,1]
	v_pk_mul_f32 v[34:35], v[20:21], v[140:141] op_sel_hi:[0,1]
	v_pk_fma_f32 v[46:47], v[24:25], v[142:143], v[46:47] op_sel:[1,0,0] op_sel_hi:[1,1,1]
	v_pk_fma_f32 v[34:35], v[20:21], v[142:143], v[34:35] op_sel:[1,0,0] op_sel_hi:[1,1,1]
	v_pk_fma_f32 v[46:47], v[26:27], v[152:153], v[46:47] op_sel_hi:[0,1,1]
	v_pk_fma_f32 v[34:35], v[22:23], v[152:153], v[34:35] op_sel_hi:[0,1,1]
	v_pk_fma_f32 v[46:47], v[26:27], v[154:155], v[46:47] op_sel:[1,0,0] op_sel_hi:[1,1,1]
	v_pk_fma_f32 v[34:35], v[22:23], v[154:155], v[34:35] op_sel:[1,0,0] op_sel_hi:[1,1,1]
	v_pk_fma_f32 v[20:21], v[176:177], v[4:5], v[20:21] op_sel_hi:[1,0,1]
	v_add_f32_dpp v28, v46, v34 row_half_mirror row_mask:0xf bank_mask:0xf
	v_add_f32_dpp v32, v47, v35 row_half_mirror row_mask:0xf bank_mask:0xf
	v_pk_fma_f32 v[22:23], v[178:179], v[4:5], v[22:23] op_sel_hi:[1,0,1]
	v_add_f32_dpp v28, v28, v28 row_ror:8 row_mask:0xf bank_mask:0xf
	v_add_f32_dpp v32, v32, v32 row_ror:8 row_mask:0xf bank_mask:0xf
	v_pk_fma_f32 v[24:25], v[176:177], v[6:7], v[24:25] op_sel_hi:[1,0,1]
	v_add_f32_dpp v28, v28, v28 quad_perm:[1,0,3,2] row_mask:0xf bank_mask:0xf
	v_add_f32_dpp v32, v32, v32 quad_perm:[1,0,3,2] row_mask:0xf bank_mask:0xf
	v_pk_fma_f32 v[26:27], v[178:179], v[6:7], v[26:27] op_sel_hi:[1,0,1]
	v_add_f32_dpp v28, v28, v28 quad_perm:[2,3,0,1] row_mask:0xf bank_mask:0xf
	v_add_f32_dpp v32, v32, v32 quad_perm:[2,3,0,1] row_mask:0xf bank_mask:0xf
	ds_read_b64 v[8:9], v196 offset:7680
	ds_read_b32 v10, v36 offset:7680
	v_add_f32_e32 v39, v32, v5
	v_mov_b32_dpp v30, v28 row_half_mirror row_mask:0xf bank_mask:0xf
	v_pk_fma_f32 v[20:21], v[84:85], v[28:29], v[20:21] op_sel_hi:[1,0,1] neg_lo:[0,1,0] neg_hi:[0,1,0]
	v_pk_fma_f32 v[22:23], v[86:87], v[28:29], v[22:23] op_sel_hi:[1,0,1] neg_lo:[0,1,0] neg_hi:[0,1,0]
	v_pk_fma_f32 v[24:25], v[84:85], v[30:31], v[24:25] op_sel_hi:[1,0,1] neg_lo:[0,1,0] neg_hi:[0,1,0]
	v_pk_fma_f32 v[26:27], v[86:87], v[30:31], v[26:27] op_sel_hi:[1,0,1] neg_lo:[0,1,0] neg_hi:[0,1,0]
	ds_write_b32 v102, v39 offset:1792
	ds_read_b128 v[140:143], v195 offset:4096
	ds_read_b128 v[152:155], v195 offset:12288
	ds_read_b128 v[176:179], v195 offset:20480
	ds_read_b128 v[84:87], v195 offset:36864
	ds_read_b64 v[4:5], v196 offset:8192
	ds_read_b32 v6, v36 offset:8192
	s_waitcnt lgkmcnt(7)
	v_pk_mul_f32 v[46:47], v[24:25], v[144:145] op_sel_hi:[0,1]
	v_pk_mul_f32 v[34:35], v[20:21], v[144:145] op_sel_hi:[0,1]
	v_pk_fma_f32 v[46:47], v[24:25], v[146:147], v[46:47] op_sel:[1,0,0] op_sel_hi:[1,1,1]
	v_pk_fma_f32 v[34:35], v[20:21], v[146:147], v[34:35] op_sel:[1,0,0] op_sel_hi:[1,1,1]
	v_pk_fma_f32 v[46:47], v[26:27], v[156:157], v[46:47] op_sel_hi:[0,1,1]
	v_pk_fma_f32 v[34:35], v[22:23], v[156:157], v[34:35] op_sel_hi:[0,1,1]
	v_pk_fma_f32 v[46:47], v[26:27], v[158:159], v[46:47] op_sel:[1,0,0] op_sel_hi:[1,1,1]
	v_pk_fma_f32 v[34:35], v[22:23], v[158:159], v[34:35] op_sel:[1,0,0] op_sel_hi:[1,1,1]
	v_pk_mul_f32 v[20:21], v[20:21], v[168:169]
	v_add_f32_dpp v28, v46, v34 row_half_mirror row_mask:0xf bank_mask:0xf
	v_add_f32_dpp v32, v47, v35 row_half_mirror row_mask:0xf bank_mask:0xf
	v_pk_mul_f32 v[22:23], v[22:23], v[170:171]
	v_add_f32_dpp v28, v28, v28 row_ror:8 row_mask:0xf bank_mask:0xf
	v_add_f32_dpp v32, v32, v32 row_ror:8 row_mask:0xf bank_mask:0xf
	v_pk_mul_f32 v[24:25], v[24:25], v[168:169]
	v_add_f32_dpp v28, v28, v28 quad_perm:[1,0,3,2] row_mask:0xf bank_mask:0xf
	v_add_f32_dpp v32, v32, v32 quad_perm:[1,0,3,2] row_mask:0xf bank_mask:0xf
	v_pk_mul_f32 v[26:27], v[26:27], v[170:171]
	v_add_f32_dpp v28, v28, v28 quad_perm:[2,3,0,1] row_mask:0xf bank_mask:0xf
	v_add_f32_dpp v32, v32, v32 quad_perm:[2,3,0,1] row_mask:0xf bank_mask:0xf
	v_pk_fma_f32 v[20:21], v[180:181], v[8:9], v[20:21] op_sel_hi:[1,0,1]
	v_mov_b32_dpp v30, v28 row_half_mirror row_mask:0xf bank_mask:0xf
	v_pk_fma_f32 v[22:23], v[182:183], v[8:9], v[22:23] op_sel_hi:[1,0,1]
	v_pk_fma_f32 v[24:25], v[180:181], v[10:11], v[24:25] op_sel_hi:[1,0,1]
	v_pk_fma_f32 v[26:27], v[182:183], v[10:11], v[26:27] op_sel_hi:[1,0,1]
	v_pk_fma_f32 v[20:21], v[88:89], v[28:29], v[20:21] op_sel_hi:[1,0,1] neg_lo:[0,1,0] neg_hi:[0,1,0]
	v_pk_fma_f32 v[22:23], v[90:91], v[28:29], v[22:23] op_sel_hi:[1,0,1] neg_lo:[0,1,0] neg_hi:[0,1,0]
	v_pk_fma_f32 v[24:25], v[88:89], v[30:31], v[24:25] op_sel_hi:[1,0,1] neg_lo:[0,1,0] neg_hi:[0,1,0]
	v_pk_fma_f32 v[26:27], v[90:91], v[30:31], v[26:27] op_sel_hi:[1,0,1] neg_lo:[0,1,0] neg_hi:[0,1,0]
	v_add_f32_e32 v39, v32, v9
	ds_write_b32 v102, v39 offset:1920
	ds_read_b128 v[144:147], v195 offset:4352
	ds_read_b128 v[156:159], v195 offset:12544
	ds_read_b128 v[180:183], v195 offset:20736
	ds_read_b128 v[88:91], v195 offset:37120
	s_waitcnt lgkmcnt(5)
	v_pk_mul_f32 v[46:47], v[24:25], v[140:141] op_sel_hi:[0,1]
	v_pk_mul_f32 v[34:35], v[20:21], v[140:141] op_sel_hi:[0,1]
	v_pk_fma_f32 v[46:47], v[24:25], v[142:143], v[46:47] op_sel:[1,0,0] op_sel_hi:[1,1,1]
	v_pk_fma_f32 v[34:35], v[20:21], v[142:143], v[34:35] op_sel:[1,0,0] op_sel_hi:[1,1,1]
	v_pk_fma_f32 v[46:47], v[26:27], v[152:153], v[46:47] op_sel_hi:[0,1,1]
	v_pk_fma_f32 v[34:35], v[22:23], v[152:153], v[34:35] op_sel_hi:[0,1,1]
	v_pk_fma_f32 v[46:47], v[26:27], v[154:155], v[46:47] op_sel:[1,0,0] op_sel_hi:[1,1,1]
	v_pk_fma_f32 v[34:35], v[22:23], v[154:155], v[34:35] op_sel:[1,0,0] op_sel_hi:[1,1,1]
	v_pk_fma_f32 v[20:21], v[176:177], v[4:5], v[20:21] op_sel_hi:[1,0,1]
	v_add_f32_dpp v28, v46, v34 row_half_mirror row_mask:0xf bank_mask:0xf
	v_add_f32_dpp v32, v47, v35 row_half_mirror row_mask:0xf bank_mask:0xf
	v_pk_fma_f32 v[22:23], v[178:179], v[4:5], v[22:23] op_sel_hi:[1,0,1]
	v_add_f32_dpp v28, v28, v28 row_ror:8 row_mask:0xf bank_mask:0xf
	v_add_f32_dpp v32, v32, v32 row_ror:8 row_mask:0xf bank_mask:0xf
	v_pk_fma_f32 v[24:25], v[176:177], v[6:7], v[24:25] op_sel_hi:[1,0,1]
	v_add_f32_dpp v28, v28, v28 quad_perm:[1,0,3,2] row_mask:0xf bank_mask:0xf
	v_add_f32_dpp v32, v32, v32 quad_perm:[1,0,3,2] row_mask:0xf bank_mask:0xf
	v_pk_fma_f32 v[26:27], v[178:179], v[6:7], v[26:27] op_sel_hi:[1,0,1]
	v_add_f32_dpp v28, v28, v28 quad_perm:[2,3,0,1] row_mask:0xf bank_mask:0xf
	v_add_f32_dpp v32, v32, v32 quad_perm:[2,3,0,1] row_mask:0xf bank_mask:0xf
	ds_read_b64 v[8:9], v196 offset:8704
	ds_read_b32 v10, v36 offset:8704
	v_add_f32_e32 v39, v32, v5
	v_mov_b32_dpp v30, v28 row_half_mirror row_mask:0xf bank_mask:0xf
	v_pk_fma_f32 v[20:21], v[84:85], v[28:29], v[20:21] op_sel_hi:[1,0,1] neg_lo:[0,1,0] neg_hi:[0,1,0]
	v_pk_fma_f32 v[22:23], v[86:87], v[28:29], v[22:23] op_sel_hi:[1,0,1] neg_lo:[0,1,0] neg_hi:[0,1,0]
	v_pk_fma_f32 v[24:25], v[84:85], v[30:31], v[24:25] op_sel_hi:[1,0,1] neg_lo:[0,1,0] neg_hi:[0,1,0]
	v_pk_fma_f32 v[26:27], v[86:87], v[30:31], v[26:27] op_sel_hi:[1,0,1] neg_lo:[0,1,0] neg_hi:[0,1,0]
	ds_write_b32 v102, v39 offset:2048
	ds_read_b128 v[140:143], v195 offset:4608
	ds_read_b128 v[152:155], v195 offset:12800
	ds_read_b128 v[176:179], v195 offset:20992
	ds_read_b128 v[84:87], v195 offset:37376
	s_waitcnt lgkmcnt(5)
	v_pk_mul_f32 v[46:47], v[24:25], v[144:145] op_sel_hi:[0,1]
	v_pk_mul_f32 v[34:35], v[20:21], v[144:145] op_sel_hi:[0,1]
	v_pk_fma_f32 v[46:47], v[24:25], v[146:147], v[46:47] op_sel:[1,0,0] op_sel_hi:[1,1,1]
	v_pk_fma_f32 v[34:35], v[20:21], v[146:147], v[34:35] op_sel:[1,0,0] op_sel_hi:[1,1,1]
	v_pk_fma_f32 v[46:47], v[26:27], v[156:157], v[46:47] op_sel_hi:[0,1,1]
	v_pk_fma_f32 v[34:35], v[22:23], v[156:157], v[34:35] op_sel_hi:[0,1,1]
	v_pk_fma_f32 v[46:47], v[26:27], v[158:159], v[46:47] op_sel:[1,0,0] op_sel_hi:[1,1,1]
	v_pk_fma_f32 v[34:35], v[22:23], v[158:159], v[34:35] op_sel:[1,0,0] op_sel_hi:[1,1,1]
	v_pk_fma_f32 v[20:21], v[180:181], v[8:9], v[20:21] op_sel_hi:[1,0,1]
	v_add_f32_dpp v28, v46, v34 row_half_mirror row_mask:0xf bank_mask:0xf
	v_add_f32_dpp v32, v47, v35 row_half_mirror row_mask:0xf bank_mask:0xf
	v_pk_fma_f32 v[22:23], v[182:183], v[8:9], v[22:23] op_sel_hi:[1,0,1]
	v_add_f32_dpp v28, v28, v28 row_ror:8 row_mask:0xf bank_mask:0xf
	v_add_f32_dpp v32, v32, v32 row_ror:8 row_mask:0xf bank_mask:0xf
	v_pk_fma_f32 v[24:25], v[180:181], v[10:11], v[24:25] op_sel_hi:[1,0,1]
	v_add_f32_dpp v28, v28, v28 quad_perm:[1,0,3,2] row_mask:0xf bank_mask:0xf
	v_add_f32_dpp v32, v32, v32 quad_perm:[1,0,3,2] row_mask:0xf bank_mask:0xf
	v_pk_fma_f32 v[26:27], v[182:183], v[10:11], v[26:27] op_sel_hi:[1,0,1]
	v_add_f32_dpp v28, v28, v28 quad_perm:[2,3,0,1] row_mask:0xf bank_mask:0xf
	v_add_f32_dpp v32, v32, v32 quad_perm:[2,3,0,1] row_mask:0xf bank_mask:0xf
	ds_read_b64 v[4:5], v196 offset:9216
	ds_read_b32 v6, v36 offset:9216
	v_add_f32_e32 v39, v32, v9
	v_mov_b32_dpp v30, v28 row_half_mirror row_mask:0xf bank_mask:0xf
	v_pk_fma_f32 v[20:21], v[88:89], v[28:29], v[20:21] op_sel_hi:[1,0,1] neg_lo:[0,1,0] neg_hi:[0,1,0]
	v_pk_fma_f32 v[22:23], v[90:91], v[28:29], v[22:23] op_sel_hi:[1,0,1] neg_lo:[0,1,0] neg_hi:[0,1,0]
	v_pk_fma_f32 v[24:25], v[88:89], v[30:31], v[24:25] op_sel_hi:[1,0,1] neg_lo:[0,1,0] neg_hi:[0,1,0]
	v_pk_fma_f32 v[26:27], v[90:91], v[30:31], v[26:27] op_sel_hi:[1,0,1] neg_lo:[0,1,0] neg_hi:[0,1,0]
	ds_write_b32 v102, v39 offset:2176
	ds_read_b128 v[144:147], v195 offset:4864
	ds_read_b128 v[156:159], v195 offset:13056
	ds_read_b128 v[168:171], v195 offset:29440
	ds_read_b128 v[180:183], v195 offset:21248
	ds_read_b128 v[88:91], v195 offset:37632
	s_waitcnt lgkmcnt(6)
	v_pk_mul_f32 v[46:47], v[24:25], v[140:141] op_sel_hi:[0,1]
	v_pk_mul_f32 v[34:35], v[20:21], v[140:141] op_sel_hi:[0,1]
	v_pk_fma_f32 v[46:47], v[24:25], v[142:143], v[46:47] op_sel:[1,0,0] op_sel_hi:[1,1,1]
	v_pk_fma_f32 v[34:35], v[20:21], v[142:143], v[34:35] op_sel:[1,0,0] op_sel_hi:[1,1,1]
	v_pk_fma_f32 v[46:47], v[26:27], v[152:153], v[46:47] op_sel_hi:[0,1,1]
	v_pk_fma_f32 v[34:35], v[22:23], v[152:153], v[34:35] op_sel_hi:[0,1,1]
	v_pk_fma_f32 v[46:47], v[26:27], v[154:155], v[46:47] op_sel:[1,0,0] op_sel_hi:[1,1,1]
	v_pk_fma_f32 v[34:35], v[22:23], v[154:155], v[34:35] op_sel:[1,0,0] op_sel_hi:[1,1,1]
	v_pk_fma_f32 v[20:21], v[176:177], v[4:5], v[20:21] op_sel_hi:[1,0,1]
	v_add_f32_dpp v28, v46, v34 row_half_mirror row_mask:0xf bank_mask:0xf
	v_add_f32_dpp v32, v47, v35 row_half_mirror row_mask:0xf bank_mask:0xf
	v_pk_fma_f32 v[22:23], v[178:179], v[4:5], v[22:23] op_sel_hi:[1,0,1]
	v_add_f32_dpp v28, v28, v28 row_ror:8 row_mask:0xf bank_mask:0xf
	v_add_f32_dpp v32, v32, v32 row_ror:8 row_mask:0xf bank_mask:0xf
	v_pk_fma_f32 v[24:25], v[176:177], v[6:7], v[24:25] op_sel_hi:[1,0,1]
	v_add_f32_dpp v28, v28, v28 quad_perm:[1,0,3,2] row_mask:0xf bank_mask:0xf
	v_add_f32_dpp v32, v32, v32 quad_perm:[1,0,3,2] row_mask:0xf bank_mask:0xf
	v_pk_fma_f32 v[26:27], v[178:179], v[6:7], v[26:27] op_sel_hi:[1,0,1]
	v_add_f32_dpp v28, v28, v28 quad_perm:[2,3,0,1] row_mask:0xf bank_mask:0xf
	v_add_f32_dpp v32, v32, v32 quad_perm:[2,3,0,1] row_mask:0xf bank_mask:0xf
	ds_read_b64 v[8:9], v196 offset:9728
	ds_read_b32 v10, v36 offset:9728
	v_add_f32_e32 v39, v32, v5
	v_mov_b32_dpp v30, v28 row_half_mirror row_mask:0xf bank_mask:0xf
	v_pk_fma_f32 v[20:21], v[84:85], v[28:29], v[20:21] op_sel_hi:[1,0,1] neg_lo:[0,1,0] neg_hi:[0,1,0]
	v_pk_fma_f32 v[22:23], v[86:87], v[28:29], v[22:23] op_sel_hi:[1,0,1] neg_lo:[0,1,0] neg_hi:[0,1,0]
	v_pk_fma_f32 v[24:25], v[84:85], v[30:31], v[24:25] op_sel_hi:[1,0,1] neg_lo:[0,1,0] neg_hi:[0,1,0]
	v_pk_fma_f32 v[26:27], v[86:87], v[30:31], v[26:27] op_sel_hi:[1,0,1] neg_lo:[0,1,0] neg_hi:[0,1,0]
	ds_write_b32 v102, v39 offset:2304
	ds_read_b128 v[140:143], v195 offset:5120
	ds_read_b128 v[152:155], v195 offset:13312
	ds_read_b128 v[176:179], v195 offset:21504
	ds_read_b128 v[84:87], v195 offset:37888
	ds_read_b64 v[4:5], v196 offset:10240
	ds_read_b32 v6, v36 offset:10240
	s_waitcnt lgkmcnt(7)
	v_pk_mul_f32 v[46:47], v[24:25], v[144:145] op_sel_hi:[0,1]
	v_pk_mul_f32 v[34:35], v[20:21], v[144:145] op_sel_hi:[0,1]
	v_pk_fma_f32 v[46:47], v[24:25], v[146:147], v[46:47] op_sel:[1,0,0] op_sel_hi:[1,1,1]
	v_pk_fma_f32 v[34:35], v[20:21], v[146:147], v[34:35] op_sel:[1,0,0] op_sel_hi:[1,1,1]
	v_pk_fma_f32 v[46:47], v[26:27], v[156:157], v[46:47] op_sel_hi:[0,1,1]
	v_pk_fma_f32 v[34:35], v[22:23], v[156:157], v[34:35] op_sel_hi:[0,1,1]
	v_pk_fma_f32 v[46:47], v[26:27], v[158:159], v[46:47] op_sel:[1,0,0] op_sel_hi:[1,1,1]
	v_pk_fma_f32 v[34:35], v[22:23], v[158:159], v[34:35] op_sel:[1,0,0] op_sel_hi:[1,1,1]
	v_pk_mul_f32 v[20:21], v[20:21], v[168:169]
	v_add_f32_dpp v28, v46, v34 row_half_mirror row_mask:0xf bank_mask:0xf
	v_add_f32_dpp v32, v47, v35 row_half_mirror row_mask:0xf bank_mask:0xf
	v_pk_mul_f32 v[22:23], v[22:23], v[170:171]
	v_add_f32_dpp v28, v28, v28 row_ror:8 row_mask:0xf bank_mask:0xf
	v_add_f32_dpp v32, v32, v32 row_ror:8 row_mask:0xf bank_mask:0xf
	v_pk_mul_f32 v[24:25], v[24:25], v[168:169]
	v_add_f32_dpp v28, v28, v28 quad_perm:[1,0,3,2] row_mask:0xf bank_mask:0xf
	v_add_f32_dpp v32, v32, v32 quad_perm:[1,0,3,2] row_mask:0xf bank_mask:0xf
	v_pk_mul_f32 v[26:27], v[26:27], v[170:171]
	v_add_f32_dpp v28, v28, v28 quad_perm:[2,3,0,1] row_mask:0xf bank_mask:0xf
	v_add_f32_dpp v32, v32, v32 quad_perm:[2,3,0,1] row_mask:0xf bank_mask:0xf
	v_pk_fma_f32 v[20:21], v[180:181], v[8:9], v[20:21] op_sel_hi:[1,0,1]
	v_mov_b32_dpp v30, v28 row_half_mirror row_mask:0xf bank_mask:0xf
	v_pk_fma_f32 v[22:23], v[182:183], v[8:9], v[22:23] op_sel_hi:[1,0,1]
	v_pk_fma_f32 v[24:25], v[180:181], v[10:11], v[24:25] op_sel_hi:[1,0,1]
	v_pk_fma_f32 v[26:27], v[182:183], v[10:11], v[26:27] op_sel_hi:[1,0,1]
	v_pk_fma_f32 v[20:21], v[88:89], v[28:29], v[20:21] op_sel_hi:[1,0,1] neg_lo:[0,1,0] neg_hi:[0,1,0]
	v_pk_fma_f32 v[22:23], v[90:91], v[28:29], v[22:23] op_sel_hi:[1,0,1] neg_lo:[0,1,0] neg_hi:[0,1,0]
	v_pk_fma_f32 v[24:25], v[88:89], v[30:31], v[24:25] op_sel_hi:[1,0,1] neg_lo:[0,1,0] neg_hi:[0,1,0]
	v_pk_fma_f32 v[26:27], v[90:91], v[30:31], v[26:27] op_sel_hi:[1,0,1] neg_lo:[0,1,0] neg_hi:[0,1,0]
	v_add_f32_e32 v39, v32, v9
	ds_write_b32 v102, v39 offset:2432
	ds_read_b128 v[144:147], v195 offset:5376
	ds_read_b128 v[156:159], v195 offset:13568
	ds_read_b128 v[180:183], v195 offset:21760
	ds_read_b128 v[88:91], v195 offset:38144
	s_waitcnt lgkmcnt(5)
	v_pk_mul_f32 v[46:47], v[24:25], v[140:141] op_sel_hi:[0,1]
	v_pk_mul_f32 v[34:35], v[20:21], v[140:141] op_sel_hi:[0,1]
	v_pk_fma_f32 v[46:47], v[24:25], v[142:143], v[46:47] op_sel:[1,0,0] op_sel_hi:[1,1,1]
	v_pk_fma_f32 v[34:35], v[20:21], v[142:143], v[34:35] op_sel:[1,0,0] op_sel_hi:[1,1,1]
	v_pk_fma_f32 v[46:47], v[26:27], v[152:153], v[46:47] op_sel_hi:[0,1,1]
	v_pk_fma_f32 v[34:35], v[22:23], v[152:153], v[34:35] op_sel_hi:[0,1,1]
	v_pk_fma_f32 v[46:47], v[26:27], v[154:155], v[46:47] op_sel:[1,0,0] op_sel_hi:[1,1,1]
	v_pk_fma_f32 v[34:35], v[22:23], v[154:155], v[34:35] op_sel:[1,0,0] op_sel_hi:[1,1,1]
	v_pk_fma_f32 v[20:21], v[176:177], v[4:5], v[20:21] op_sel_hi:[1,0,1]
	v_add_f32_dpp v28, v46, v34 row_half_mirror row_mask:0xf bank_mask:0xf
	v_add_f32_dpp v32, v47, v35 row_half_mirror row_mask:0xf bank_mask:0xf
	v_pk_fma_f32 v[22:23], v[178:179], v[4:5], v[22:23] op_sel_hi:[1,0,1]
	v_add_f32_dpp v28, v28, v28 row_ror:8 row_mask:0xf bank_mask:0xf
	v_add_f32_dpp v32, v32, v32 row_ror:8 row_mask:0xf bank_mask:0xf
	v_pk_fma_f32 v[24:25], v[176:177], v[6:7], v[24:25] op_sel_hi:[1,0,1]
	v_add_f32_dpp v28, v28, v28 quad_perm:[1,0,3,2] row_mask:0xf bank_mask:0xf
	v_add_f32_dpp v32, v32, v32 quad_perm:[1,0,3,2] row_mask:0xf bank_mask:0xf
	v_pk_fma_f32 v[26:27], v[178:179], v[6:7], v[26:27] op_sel_hi:[1,0,1]
	v_add_f32_dpp v28, v28, v28 quad_perm:[2,3,0,1] row_mask:0xf bank_mask:0xf
	v_add_f32_dpp v32, v32, v32 quad_perm:[2,3,0,1] row_mask:0xf bank_mask:0xf
	ds_read_b64 v[8:9], v196 offset:10752
	ds_read_b32 v10, v36 offset:10752
	v_add_f32_e32 v39, v32, v5
	v_mov_b32_dpp v30, v28 row_half_mirror row_mask:0xf bank_mask:0xf
	v_pk_fma_f32 v[20:21], v[84:85], v[28:29], v[20:21] op_sel_hi:[1,0,1] neg_lo:[0,1,0] neg_hi:[0,1,0]
	v_pk_fma_f32 v[22:23], v[86:87], v[28:29], v[22:23] op_sel_hi:[1,0,1] neg_lo:[0,1,0] neg_hi:[0,1,0]
	v_pk_fma_f32 v[24:25], v[84:85], v[30:31], v[24:25] op_sel_hi:[1,0,1] neg_lo:[0,1,0] neg_hi:[0,1,0]
	v_pk_fma_f32 v[26:27], v[86:87], v[30:31], v[26:27] op_sel_hi:[1,0,1] neg_lo:[0,1,0] neg_hi:[0,1,0]
	ds_write_b32 v102, v39 offset:2560
	ds_read_b128 v[140:143], v195 offset:5632
	ds_read_b128 v[152:155], v195 offset:13824
	ds_read_b128 v[176:179], v195 offset:22016
	ds_read_b128 v[84:87], v195 offset:38400
	s_waitcnt lgkmcnt(5)
	v_pk_mul_f32 v[46:47], v[24:25], v[144:145] op_sel_hi:[0,1]
	v_pk_mul_f32 v[34:35], v[20:21], v[144:145] op_sel_hi:[0,1]
	v_pk_fma_f32 v[46:47], v[24:25], v[146:147], v[46:47] op_sel:[1,0,0] op_sel_hi:[1,1,1]
	v_pk_fma_f32 v[34:35], v[20:21], v[146:147], v[34:35] op_sel:[1,0,0] op_sel_hi:[1,1,1]
	v_pk_fma_f32 v[46:47], v[26:27], v[156:157], v[46:47] op_sel_hi:[0,1,1]
	v_pk_fma_f32 v[34:35], v[22:23], v[156:157], v[34:35] op_sel_hi:[0,1,1]
	v_pk_fma_f32 v[46:47], v[26:27], v[158:159], v[46:47] op_sel:[1,0,0] op_sel_hi:[1,1,1]
	v_pk_fma_f32 v[34:35], v[22:23], v[158:159], v[34:35] op_sel:[1,0,0] op_sel_hi:[1,1,1]
	v_pk_fma_f32 v[20:21], v[180:181], v[8:9], v[20:21] op_sel_hi:[1,0,1]
	v_add_f32_dpp v28, v46, v34 row_half_mirror row_mask:0xf bank_mask:0xf
	v_add_f32_dpp v32, v47, v35 row_half_mirror row_mask:0xf bank_mask:0xf
	v_pk_fma_f32 v[22:23], v[182:183], v[8:9], v[22:23] op_sel_hi:[1,0,1]
	v_add_f32_dpp v28, v28, v28 row_ror:8 row_mask:0xf bank_mask:0xf
	v_add_f32_dpp v32, v32, v32 row_ror:8 row_mask:0xf bank_mask:0xf
	v_pk_fma_f32 v[24:25], v[180:181], v[10:11], v[24:25] op_sel_hi:[1,0,1]
	v_add_f32_dpp v28, v28, v28 quad_perm:[1,0,3,2] row_mask:0xf bank_mask:0xf
	v_add_f32_dpp v32, v32, v32 quad_perm:[1,0,3,2] row_mask:0xf bank_mask:0xf
	v_pk_fma_f32 v[26:27], v[182:183], v[10:11], v[26:27] op_sel_hi:[1,0,1]
	v_add_f32_dpp v28, v28, v28 quad_perm:[2,3,0,1] row_mask:0xf bank_mask:0xf
	v_add_f32_dpp v32, v32, v32 quad_perm:[2,3,0,1] row_mask:0xf bank_mask:0xf
	ds_read_b64 v[4:5], v196 offset:11264
	ds_read_b32 v6, v36 offset:11264
	v_add_f32_e32 v39, v32, v9
	v_mov_b32_dpp v30, v28 row_half_mirror row_mask:0xf bank_mask:0xf
	v_pk_fma_f32 v[20:21], v[88:89], v[28:29], v[20:21] op_sel_hi:[1,0,1] neg_lo:[0,1,0] neg_hi:[0,1,0]
	v_pk_fma_f32 v[22:23], v[90:91], v[28:29], v[22:23] op_sel_hi:[1,0,1] neg_lo:[0,1,0] neg_hi:[0,1,0]
	v_pk_fma_f32 v[24:25], v[88:89], v[30:31], v[24:25] op_sel_hi:[1,0,1] neg_lo:[0,1,0] neg_hi:[0,1,0]
	v_pk_fma_f32 v[26:27], v[90:91], v[30:31], v[26:27] op_sel_hi:[1,0,1] neg_lo:[0,1,0] neg_hi:[0,1,0]
	ds_write_b32 v102, v39 offset:2688
	ds_read_b128 v[144:147], v195 offset:5888
	ds_read_b128 v[156:159], v195 offset:14080
	ds_read_b128 v[168:171], v195 offset:30464
	ds_read_b128 v[180:183], v195 offset:22272
	ds_read_b128 v[88:91], v195 offset:38656
	s_waitcnt lgkmcnt(6)
	v_pk_mul_f32 v[46:47], v[24:25], v[140:141] op_sel_hi:[0,1]
	v_pk_mul_f32 v[34:35], v[20:21], v[140:141] op_sel_hi:[0,1]
	v_pk_fma_f32 v[46:47], v[24:25], v[142:143], v[46:47] op_sel:[1,0,0] op_sel_hi:[1,1,1]
	v_pk_fma_f32 v[34:35], v[20:21], v[142:143], v[34:35] op_sel:[1,0,0] op_sel_hi:[1,1,1]
	v_pk_fma_f32 v[46:47], v[26:27], v[152:153], v[46:47] op_sel_hi:[0,1,1]
	v_pk_fma_f32 v[34:35], v[22:23], v[152:153], v[34:35] op_sel_hi:[0,1,1]
	v_pk_fma_f32 v[46:47], v[26:27], v[154:155], v[46:47] op_sel:[1,0,0] op_sel_hi:[1,1,1]
	v_pk_fma_f32 v[34:35], v[22:23], v[154:155], v[34:35] op_sel:[1,0,0] op_sel_hi:[1,1,1]
	v_pk_fma_f32 v[20:21], v[176:177], v[4:5], v[20:21] op_sel_hi:[1,0,1]
	v_add_f32_dpp v28, v46, v34 row_half_mirror row_mask:0xf bank_mask:0xf
	v_add_f32_dpp v32, v47, v35 row_half_mirror row_mask:0xf bank_mask:0xf
	v_pk_fma_f32 v[22:23], v[178:179], v[4:5], v[22:23] op_sel_hi:[1,0,1]
	v_add_f32_dpp v28, v28, v28 row_ror:8 row_mask:0xf bank_mask:0xf
	v_add_f32_dpp v32, v32, v32 row_ror:8 row_mask:0xf bank_mask:0xf
	v_pk_fma_f32 v[24:25], v[176:177], v[6:7], v[24:25] op_sel_hi:[1,0,1]
	v_add_f32_dpp v28, v28, v28 quad_perm:[1,0,3,2] row_mask:0xf bank_mask:0xf
	v_add_f32_dpp v32, v32, v32 quad_perm:[1,0,3,2] row_mask:0xf bank_mask:0xf
	v_pk_fma_f32 v[26:27], v[178:179], v[6:7], v[26:27] op_sel_hi:[1,0,1]
	v_add_f32_dpp v28, v28, v28 quad_perm:[2,3,0,1] row_mask:0xf bank_mask:0xf
	v_add_f32_dpp v32, v32, v32 quad_perm:[2,3,0,1] row_mask:0xf bank_mask:0xf
	ds_read_b64 v[8:9], v196 offset:11776
	ds_read_b32 v10, v36 offset:11776
	v_add_f32_e32 v39, v32, v5
	v_mov_b32_dpp v30, v28 row_half_mirror row_mask:0xf bank_mask:0xf
	v_pk_fma_f32 v[20:21], v[84:85], v[28:29], v[20:21] op_sel_hi:[1,0,1] neg_lo:[0,1,0] neg_hi:[0,1,0]
	v_pk_fma_f32 v[22:23], v[86:87], v[28:29], v[22:23] op_sel_hi:[1,0,1] neg_lo:[0,1,0] neg_hi:[0,1,0]
	v_pk_fma_f32 v[24:25], v[84:85], v[30:31], v[24:25] op_sel_hi:[1,0,1] neg_lo:[0,1,0] neg_hi:[0,1,0]
	v_pk_fma_f32 v[26:27], v[86:87], v[30:31], v[26:27] op_sel_hi:[1,0,1] neg_lo:[0,1,0] neg_hi:[0,1,0]
	ds_write_b32 v102, v39 offset:2816
	ds_read_b128 v[140:143], v195 offset:6144
	ds_read_b128 v[152:155], v195 offset:14336
	ds_read_b128 v[176:179], v195 offset:22528
	ds_read_b128 v[84:87], v195 offset:38912
	ds_read_b64 v[4:5], v196 offset:12288
	ds_read_b32 v6, v36 offset:12288
	s_waitcnt lgkmcnt(7)
	v_pk_mul_f32 v[46:47], v[24:25], v[144:145] op_sel_hi:[0,1]
	v_pk_mul_f32 v[34:35], v[20:21], v[144:145] op_sel_hi:[0,1]
	v_pk_fma_f32 v[46:47], v[24:25], v[146:147], v[46:47] op_sel:[1,0,0] op_sel_hi:[1,1,1]
	v_pk_fma_f32 v[34:35], v[20:21], v[146:147], v[34:35] op_sel:[1,0,0] op_sel_hi:[1,1,1]
	v_pk_fma_f32 v[46:47], v[26:27], v[156:157], v[46:47] op_sel_hi:[0,1,1]
	v_pk_fma_f32 v[34:35], v[22:23], v[156:157], v[34:35] op_sel_hi:[0,1,1]
	v_pk_fma_f32 v[46:47], v[26:27], v[158:159], v[46:47] op_sel:[1,0,0] op_sel_hi:[1,1,1]
	v_pk_fma_f32 v[34:35], v[22:23], v[158:159], v[34:35] op_sel:[1,0,0] op_sel_hi:[1,1,1]
	v_pk_mul_f32 v[20:21], v[20:21], v[168:169]
	v_add_f32_dpp v28, v46, v34 row_half_mirror row_mask:0xf bank_mask:0xf
	v_add_f32_dpp v32, v47, v35 row_half_mirror row_mask:0xf bank_mask:0xf
	v_pk_mul_f32 v[22:23], v[22:23], v[170:171]
	v_add_f32_dpp v28, v28, v28 row_ror:8 row_mask:0xf bank_mask:0xf
	v_add_f32_dpp v32, v32, v32 row_ror:8 row_mask:0xf bank_mask:0xf
	v_pk_mul_f32 v[24:25], v[24:25], v[168:169]
	v_add_f32_dpp v28, v28, v28 quad_perm:[1,0,3,2] row_mask:0xf bank_mask:0xf
	v_add_f32_dpp v32, v32, v32 quad_perm:[1,0,3,2] row_mask:0xf bank_mask:0xf
	v_pk_mul_f32 v[26:27], v[26:27], v[170:171]
	v_add_f32_dpp v28, v28, v28 quad_perm:[2,3,0,1] row_mask:0xf bank_mask:0xf
	v_add_f32_dpp v32, v32, v32 quad_perm:[2,3,0,1] row_mask:0xf bank_mask:0xf
	v_pk_fma_f32 v[20:21], v[180:181], v[8:9], v[20:21] op_sel_hi:[1,0,1]
	v_mov_b32_dpp v30, v28 row_half_mirror row_mask:0xf bank_mask:0xf
	v_pk_fma_f32 v[22:23], v[182:183], v[8:9], v[22:23] op_sel_hi:[1,0,1]
	v_pk_fma_f32 v[24:25], v[180:181], v[10:11], v[24:25] op_sel_hi:[1,0,1]
	v_pk_fma_f32 v[26:27], v[182:183], v[10:11], v[26:27] op_sel_hi:[1,0,1]
	v_pk_fma_f32 v[20:21], v[88:89], v[28:29], v[20:21] op_sel_hi:[1,0,1] neg_lo:[0,1,0] neg_hi:[0,1,0]
	v_pk_fma_f32 v[22:23], v[90:91], v[28:29], v[22:23] op_sel_hi:[1,0,1] neg_lo:[0,1,0] neg_hi:[0,1,0]
	v_pk_fma_f32 v[24:25], v[88:89], v[30:31], v[24:25] op_sel_hi:[1,0,1] neg_lo:[0,1,0] neg_hi:[0,1,0]
	v_pk_fma_f32 v[26:27], v[90:91], v[30:31], v[26:27] op_sel_hi:[1,0,1] neg_lo:[0,1,0] neg_hi:[0,1,0]
	v_add_f32_e32 v39, v32, v9
	ds_write_b32 v102, v39 offset:2944
	ds_read_b128 v[144:147], v195 offset:6400
	ds_read_b128 v[156:159], v195 offset:14592
	ds_read_b128 v[180:183], v195 offset:22784
	ds_read_b128 v[88:91], v195 offset:39168
	s_waitcnt lgkmcnt(5)
	v_pk_mul_f32 v[46:47], v[24:25], v[140:141] op_sel_hi:[0,1]
	v_pk_mul_f32 v[34:35], v[20:21], v[140:141] op_sel_hi:[0,1]
	v_pk_fma_f32 v[46:47], v[24:25], v[142:143], v[46:47] op_sel:[1,0,0] op_sel_hi:[1,1,1]
	v_pk_fma_f32 v[34:35], v[20:21], v[142:143], v[34:35] op_sel:[1,0,0] op_sel_hi:[1,1,1]
	v_pk_fma_f32 v[46:47], v[26:27], v[152:153], v[46:47] op_sel_hi:[0,1,1]
	v_pk_fma_f32 v[34:35], v[22:23], v[152:153], v[34:35] op_sel_hi:[0,1,1]
	v_pk_fma_f32 v[46:47], v[26:27], v[154:155], v[46:47] op_sel:[1,0,0] op_sel_hi:[1,1,1]
	v_pk_fma_f32 v[34:35], v[22:23], v[154:155], v[34:35] op_sel:[1,0,0] op_sel_hi:[1,1,1]
	v_pk_fma_f32 v[20:21], v[176:177], v[4:5], v[20:21] op_sel_hi:[1,0,1]
	v_add_f32_dpp v28, v46, v34 row_half_mirror row_mask:0xf bank_mask:0xf
	v_add_f32_dpp v32, v47, v35 row_half_mirror row_mask:0xf bank_mask:0xf
	v_pk_fma_f32 v[22:23], v[178:179], v[4:5], v[22:23] op_sel_hi:[1,0,1]
	v_add_f32_dpp v28, v28, v28 row_ror:8 row_mask:0xf bank_mask:0xf
	v_add_f32_dpp v32, v32, v32 row_ror:8 row_mask:0xf bank_mask:0xf
	v_pk_fma_f32 v[24:25], v[176:177], v[6:7], v[24:25] op_sel_hi:[1,0,1]
	v_add_f32_dpp v28, v28, v28 quad_perm:[1,0,3,2] row_mask:0xf bank_mask:0xf
	v_add_f32_dpp v32, v32, v32 quad_perm:[1,0,3,2] row_mask:0xf bank_mask:0xf
	v_pk_fma_f32 v[26:27], v[178:179], v[6:7], v[26:27] op_sel_hi:[1,0,1]
	v_add_f32_dpp v28, v28, v28 quad_perm:[2,3,0,1] row_mask:0xf bank_mask:0xf
	v_add_f32_dpp v32, v32, v32 quad_perm:[2,3,0,1] row_mask:0xf bank_mask:0xf
	ds_read_b64 v[8:9], v196 offset:12800
	ds_read_b32 v10, v36 offset:12800
	v_add_f32_e32 v39, v32, v5
	v_mov_b32_dpp v30, v28 row_half_mirror row_mask:0xf bank_mask:0xf
	v_pk_fma_f32 v[20:21], v[84:85], v[28:29], v[20:21] op_sel_hi:[1,0,1] neg_lo:[0,1,0] neg_hi:[0,1,0]
	v_pk_fma_f32 v[22:23], v[86:87], v[28:29], v[22:23] op_sel_hi:[1,0,1] neg_lo:[0,1,0] neg_hi:[0,1,0]
	v_pk_fma_f32 v[24:25], v[84:85], v[30:31], v[24:25] op_sel_hi:[1,0,1] neg_lo:[0,1,0] neg_hi:[0,1,0]
	v_pk_fma_f32 v[26:27], v[86:87], v[30:31], v[26:27] op_sel_hi:[1,0,1] neg_lo:[0,1,0] neg_hi:[0,1,0]
	ds_write_b32 v102, v39 offset:3072
	ds_read_b128 v[140:143], v195 offset:6656
	ds_read_b128 v[152:155], v195 offset:14848
	ds_read_b128 v[176:179], v195 offset:23040
	ds_read_b128 v[84:87], v195 offset:39424
	s_waitcnt lgkmcnt(5)
	v_pk_mul_f32 v[46:47], v[24:25], v[144:145] op_sel_hi:[0,1]
	v_pk_mul_f32 v[34:35], v[20:21], v[144:145] op_sel_hi:[0,1]
	v_pk_fma_f32 v[46:47], v[24:25], v[146:147], v[46:47] op_sel:[1,0,0] op_sel_hi:[1,1,1]
	v_pk_fma_f32 v[34:35], v[20:21], v[146:147], v[34:35] op_sel:[1,0,0] op_sel_hi:[1,1,1]
	v_pk_fma_f32 v[46:47], v[26:27], v[156:157], v[46:47] op_sel_hi:[0,1,1]
	v_pk_fma_f32 v[34:35], v[22:23], v[156:157], v[34:35] op_sel_hi:[0,1,1]
	v_pk_fma_f32 v[46:47], v[26:27], v[158:159], v[46:47] op_sel:[1,0,0] op_sel_hi:[1,1,1]
	v_pk_fma_f32 v[34:35], v[22:23], v[158:159], v[34:35] op_sel:[1,0,0] op_sel_hi:[1,1,1]
	v_pk_fma_f32 v[20:21], v[180:181], v[8:9], v[20:21] op_sel_hi:[1,0,1]
	v_add_f32_dpp v28, v46, v34 row_half_mirror row_mask:0xf bank_mask:0xf
	v_add_f32_dpp v32, v47, v35 row_half_mirror row_mask:0xf bank_mask:0xf
	v_pk_fma_f32 v[22:23], v[182:183], v[8:9], v[22:23] op_sel_hi:[1,0,1]
	v_add_f32_dpp v28, v28, v28 row_ror:8 row_mask:0xf bank_mask:0xf
	v_add_f32_dpp v32, v32, v32 row_ror:8 row_mask:0xf bank_mask:0xf
	v_pk_fma_f32 v[24:25], v[180:181], v[10:11], v[24:25] op_sel_hi:[1,0,1]
	v_add_f32_dpp v28, v28, v28 quad_perm:[1,0,3,2] row_mask:0xf bank_mask:0xf
	v_add_f32_dpp v32, v32, v32 quad_perm:[1,0,3,2] row_mask:0xf bank_mask:0xf
	v_pk_fma_f32 v[26:27], v[182:183], v[10:11], v[26:27] op_sel_hi:[1,0,1]
	v_add_f32_dpp v28, v28, v28 quad_perm:[2,3,0,1] row_mask:0xf bank_mask:0xf
	v_add_f32_dpp v32, v32, v32 quad_perm:[2,3,0,1] row_mask:0xf bank_mask:0xf
	ds_read_b64 v[4:5], v196 offset:13312
	ds_read_b32 v6, v36 offset:13312
	v_add_f32_e32 v39, v32, v9
	v_mov_b32_dpp v30, v28 row_half_mirror row_mask:0xf bank_mask:0xf
	v_pk_fma_f32 v[20:21], v[88:89], v[28:29], v[20:21] op_sel_hi:[1,0,1] neg_lo:[0,1,0] neg_hi:[0,1,0]
	v_pk_fma_f32 v[22:23], v[90:91], v[28:29], v[22:23] op_sel_hi:[1,0,1] neg_lo:[0,1,0] neg_hi:[0,1,0]
	v_pk_fma_f32 v[24:25], v[88:89], v[30:31], v[24:25] op_sel_hi:[1,0,1] neg_lo:[0,1,0] neg_hi:[0,1,0]
	v_pk_fma_f32 v[26:27], v[90:91], v[30:31], v[26:27] op_sel_hi:[1,0,1] neg_lo:[0,1,0] neg_hi:[0,1,0]
	ds_write_b32 v102, v39 offset:3200
	ds_read_b128 v[144:147], v195 offset:6912
	ds_read_b128 v[156:159], v195 offset:15104
	ds_read_b128 v[168:171], v195 offset:31488
	ds_read_b128 v[180:183], v195 offset:23296
	ds_read_b128 v[88:91], v195 offset:39680
	s_waitcnt lgkmcnt(6)
	v_pk_mul_f32 v[46:47], v[24:25], v[140:141] op_sel_hi:[0,1]
	v_pk_mul_f32 v[34:35], v[20:21], v[140:141] op_sel_hi:[0,1]
	v_pk_fma_f32 v[46:47], v[24:25], v[142:143], v[46:47] op_sel:[1,0,0] op_sel_hi:[1,1,1]
	v_pk_fma_f32 v[34:35], v[20:21], v[142:143], v[34:35] op_sel:[1,0,0] op_sel_hi:[1,1,1]
	v_pk_fma_f32 v[46:47], v[26:27], v[152:153], v[46:47] op_sel_hi:[0,1,1]
	v_pk_fma_f32 v[34:35], v[22:23], v[152:153], v[34:35] op_sel_hi:[0,1,1]
	v_pk_fma_f32 v[46:47], v[26:27], v[154:155], v[46:47] op_sel:[1,0,0] op_sel_hi:[1,1,1]
	v_pk_fma_f32 v[34:35], v[22:23], v[154:155], v[34:35] op_sel:[1,0,0] op_sel_hi:[1,1,1]
	v_pk_fma_f32 v[20:21], v[176:177], v[4:5], v[20:21] op_sel_hi:[1,0,1]
	v_add_f32_dpp v28, v46, v34 row_half_mirror row_mask:0xf bank_mask:0xf
	v_add_f32_dpp v32, v47, v35 row_half_mirror row_mask:0xf bank_mask:0xf
	v_pk_fma_f32 v[22:23], v[178:179], v[4:5], v[22:23] op_sel_hi:[1,0,1]
	v_add_f32_dpp v28, v28, v28 row_ror:8 row_mask:0xf bank_mask:0xf
	v_add_f32_dpp v32, v32, v32 row_ror:8 row_mask:0xf bank_mask:0xf
	v_pk_fma_f32 v[24:25], v[176:177], v[6:7], v[24:25] op_sel_hi:[1,0,1]
	v_add_f32_dpp v28, v28, v28 quad_perm:[1,0,3,2] row_mask:0xf bank_mask:0xf
	v_add_f32_dpp v32, v32, v32 quad_perm:[1,0,3,2] row_mask:0xf bank_mask:0xf
	v_pk_fma_f32 v[26:27], v[178:179], v[6:7], v[26:27] op_sel_hi:[1,0,1]
	v_add_f32_dpp v28, v28, v28 quad_perm:[2,3,0,1] row_mask:0xf bank_mask:0xf
	v_add_f32_dpp v32, v32, v32 quad_perm:[2,3,0,1] row_mask:0xf bank_mask:0xf
	ds_read_b64 v[8:9], v196 offset:13824
	ds_read_b32 v10, v36 offset:13824
	v_add_f32_e32 v39, v32, v5
	v_mov_b32_dpp v30, v28 row_half_mirror row_mask:0xf bank_mask:0xf
	v_pk_fma_f32 v[20:21], v[84:85], v[28:29], v[20:21] op_sel_hi:[1,0,1] neg_lo:[0,1,0] neg_hi:[0,1,0]
	v_pk_fma_f32 v[22:23], v[86:87], v[28:29], v[22:23] op_sel_hi:[1,0,1] neg_lo:[0,1,0] neg_hi:[0,1,0]
	v_pk_fma_f32 v[24:25], v[84:85], v[30:31], v[24:25] op_sel_hi:[1,0,1] neg_lo:[0,1,0] neg_hi:[0,1,0]
	v_pk_fma_f32 v[26:27], v[86:87], v[30:31], v[26:27] op_sel_hi:[1,0,1] neg_lo:[0,1,0] neg_hi:[0,1,0]
	ds_write_b32 v102, v39 offset:3328
	ds_read_b128 v[140:143], v195 offset:7168
	ds_read_b128 v[152:155], v195 offset:15360
	ds_read_b128 v[176:179], v195 offset:23552
	ds_read_b128 v[84:87], v195 offset:39936
	ds_read_b64 v[4:5], v196 offset:14336
	ds_read_b32 v6, v36 offset:14336
	s_waitcnt lgkmcnt(7)
	v_pk_mul_f32 v[46:47], v[24:25], v[144:145] op_sel_hi:[0,1]
	v_pk_mul_f32 v[34:35], v[20:21], v[144:145] op_sel_hi:[0,1]
	v_pk_fma_f32 v[46:47], v[24:25], v[146:147], v[46:47] op_sel:[1,0,0] op_sel_hi:[1,1,1]
	v_pk_fma_f32 v[34:35], v[20:21], v[146:147], v[34:35] op_sel:[1,0,0] op_sel_hi:[1,1,1]
	v_pk_fma_f32 v[46:47], v[26:27], v[156:157], v[46:47] op_sel_hi:[0,1,1]
	v_pk_fma_f32 v[34:35], v[22:23], v[156:157], v[34:35] op_sel_hi:[0,1,1]
	v_pk_fma_f32 v[46:47], v[26:27], v[158:159], v[46:47] op_sel:[1,0,0] op_sel_hi:[1,1,1]
	v_pk_fma_f32 v[34:35], v[22:23], v[158:159], v[34:35] op_sel:[1,0,0] op_sel_hi:[1,1,1]
	v_pk_mul_f32 v[20:21], v[20:21], v[168:169]
	v_add_f32_dpp v28, v46, v34 row_half_mirror row_mask:0xf bank_mask:0xf
	v_add_f32_dpp v32, v47, v35 row_half_mirror row_mask:0xf bank_mask:0xf
	v_pk_mul_f32 v[22:23], v[22:23], v[170:171]
	v_add_f32_dpp v28, v28, v28 row_ror:8 row_mask:0xf bank_mask:0xf
	v_add_f32_dpp v32, v32, v32 row_ror:8 row_mask:0xf bank_mask:0xf
	v_pk_mul_f32 v[24:25], v[24:25], v[168:169]
	v_add_f32_dpp v28, v28, v28 quad_perm:[1,0,3,2] row_mask:0xf bank_mask:0xf
	v_add_f32_dpp v32, v32, v32 quad_perm:[1,0,3,2] row_mask:0xf bank_mask:0xf
	v_pk_mul_f32 v[26:27], v[26:27], v[170:171]
	v_add_f32_dpp v28, v28, v28 quad_perm:[2,3,0,1] row_mask:0xf bank_mask:0xf
	v_add_f32_dpp v32, v32, v32 quad_perm:[2,3,0,1] row_mask:0xf bank_mask:0xf
	v_pk_fma_f32 v[20:21], v[180:181], v[8:9], v[20:21] op_sel_hi:[1,0,1]
	v_mov_b32_dpp v30, v28 row_half_mirror row_mask:0xf bank_mask:0xf
	v_pk_fma_f32 v[22:23], v[182:183], v[8:9], v[22:23] op_sel_hi:[1,0,1]
	v_pk_fma_f32 v[24:25], v[180:181], v[10:11], v[24:25] op_sel_hi:[1,0,1]
	v_pk_fma_f32 v[26:27], v[182:183], v[10:11], v[26:27] op_sel_hi:[1,0,1]
	v_pk_fma_f32 v[20:21], v[88:89], v[28:29], v[20:21] op_sel_hi:[1,0,1] neg_lo:[0,1,0] neg_hi:[0,1,0]
	v_pk_fma_f32 v[22:23], v[90:91], v[28:29], v[22:23] op_sel_hi:[1,0,1] neg_lo:[0,1,0] neg_hi:[0,1,0]
	v_pk_fma_f32 v[24:25], v[88:89], v[30:31], v[24:25] op_sel_hi:[1,0,1] neg_lo:[0,1,0] neg_hi:[0,1,0]
	v_pk_fma_f32 v[26:27], v[90:91], v[30:31], v[26:27] op_sel_hi:[1,0,1] neg_lo:[0,1,0] neg_hi:[0,1,0]
	v_add_f32_e32 v39, v32, v9
	ds_write_b32 v102, v39 offset:3456
	ds_read_b128 v[144:147], v195 offset:7424
	ds_read_b128 v[156:159], v195 offset:15616
	ds_read_b128 v[180:183], v195 offset:23808
	ds_read_b128 v[88:91], v195 offset:40192
	s_waitcnt lgkmcnt(5)
	v_pk_mul_f32 v[46:47], v[24:25], v[140:141] op_sel_hi:[0,1]
	v_pk_mul_f32 v[34:35], v[20:21], v[140:141] op_sel_hi:[0,1]
	v_pk_fma_f32 v[46:47], v[24:25], v[142:143], v[46:47] op_sel:[1,0,0] op_sel_hi:[1,1,1]
	v_pk_fma_f32 v[34:35], v[20:21], v[142:143], v[34:35] op_sel:[1,0,0] op_sel_hi:[1,1,1]
	v_pk_fma_f32 v[46:47], v[26:27], v[152:153], v[46:47] op_sel_hi:[0,1,1]
	v_pk_fma_f32 v[34:35], v[22:23], v[152:153], v[34:35] op_sel_hi:[0,1,1]
	v_pk_fma_f32 v[46:47], v[26:27], v[154:155], v[46:47] op_sel:[1,0,0] op_sel_hi:[1,1,1]
	v_pk_fma_f32 v[34:35], v[22:23], v[154:155], v[34:35] op_sel:[1,0,0] op_sel_hi:[1,1,1]
	v_pk_fma_f32 v[20:21], v[176:177], v[4:5], v[20:21] op_sel_hi:[1,0,1]
	v_add_f32_dpp v28, v46, v34 row_half_mirror row_mask:0xf bank_mask:0xf
	v_add_f32_dpp v32, v47, v35 row_half_mirror row_mask:0xf bank_mask:0xf
	v_pk_fma_f32 v[22:23], v[178:179], v[4:5], v[22:23] op_sel_hi:[1,0,1]
	v_add_f32_dpp v28, v28, v28 row_ror:8 row_mask:0xf bank_mask:0xf
	v_add_f32_dpp v32, v32, v32 row_ror:8 row_mask:0xf bank_mask:0xf
	v_pk_fma_f32 v[24:25], v[176:177], v[6:7], v[24:25] op_sel_hi:[1,0,1]
	v_add_f32_dpp v28, v28, v28 quad_perm:[1,0,3,2] row_mask:0xf bank_mask:0xf
	v_add_f32_dpp v32, v32, v32 quad_perm:[1,0,3,2] row_mask:0xf bank_mask:0xf
	v_pk_fma_f32 v[26:27], v[178:179], v[6:7], v[26:27] op_sel_hi:[1,0,1]
	v_add_f32_dpp v28, v28, v28 quad_perm:[2,3,0,1] row_mask:0xf bank_mask:0xf
	v_add_f32_dpp v32, v32, v32 quad_perm:[2,3,0,1] row_mask:0xf bank_mask:0xf
	ds_read_b64 v[8:9], v196 offset:14848
	ds_read_b32 v10, v36 offset:14848
	v_add_f32_e32 v39, v32, v5
	v_mov_b32_dpp v30, v28 row_half_mirror row_mask:0xf bank_mask:0xf
	v_pk_fma_f32 v[20:21], v[84:85], v[28:29], v[20:21] op_sel_hi:[1,0,1] neg_lo:[0,1,0] neg_hi:[0,1,0]
	v_pk_fma_f32 v[22:23], v[86:87], v[28:29], v[22:23] op_sel_hi:[1,0,1] neg_lo:[0,1,0] neg_hi:[0,1,0]
	v_pk_fma_f32 v[24:25], v[84:85], v[30:31], v[24:25] op_sel_hi:[1,0,1] neg_lo:[0,1,0] neg_hi:[0,1,0]
	v_pk_fma_f32 v[26:27], v[86:87], v[30:31], v[26:27] op_sel_hi:[1,0,1] neg_lo:[0,1,0] neg_hi:[0,1,0]
	ds_write_b32 v102, v39 offset:3584
	ds_read_b128 v[140:143], v195 offset:7680
	ds_read_b128 v[152:155], v195 offset:15872
	ds_read_b128 v[176:179], v195 offset:24064
	ds_read_b128 v[84:87], v195 offset:40448
	s_waitcnt lgkmcnt(5)
	v_pk_mul_f32 v[46:47], v[24:25], v[144:145] op_sel_hi:[0,1]
	v_pk_mul_f32 v[34:35], v[20:21], v[144:145] op_sel_hi:[0,1]
	v_pk_fma_f32 v[46:47], v[24:25], v[146:147], v[46:47] op_sel:[1,0,0] op_sel_hi:[1,1,1]
	v_pk_fma_f32 v[34:35], v[20:21], v[146:147], v[34:35] op_sel:[1,0,0] op_sel_hi:[1,1,1]
	v_pk_fma_f32 v[46:47], v[26:27], v[156:157], v[46:47] op_sel_hi:[0,1,1]
	v_pk_fma_f32 v[34:35], v[22:23], v[156:157], v[34:35] op_sel_hi:[0,1,1]
	v_pk_fma_f32 v[46:47], v[26:27], v[158:159], v[46:47] op_sel:[1,0,0] op_sel_hi:[1,1,1]
	v_pk_fma_f32 v[34:35], v[22:23], v[158:159], v[34:35] op_sel:[1,0,0] op_sel_hi:[1,1,1]
	v_pk_fma_f32 v[20:21], v[180:181], v[8:9], v[20:21] op_sel_hi:[1,0,1]
	v_add_f32_dpp v28, v46, v34 row_half_mirror row_mask:0xf bank_mask:0xf
	v_add_f32_dpp v32, v47, v35 row_half_mirror row_mask:0xf bank_mask:0xf
	v_pk_fma_f32 v[22:23], v[182:183], v[8:9], v[22:23] op_sel_hi:[1,0,1]
	v_add_f32_dpp v28, v28, v28 row_ror:8 row_mask:0xf bank_mask:0xf
	v_add_f32_dpp v32, v32, v32 row_ror:8 row_mask:0xf bank_mask:0xf
	v_pk_fma_f32 v[24:25], v[180:181], v[10:11], v[24:25] op_sel_hi:[1,0,1]
	v_add_f32_dpp v28, v28, v28 quad_perm:[1,0,3,2] row_mask:0xf bank_mask:0xf
	v_add_f32_dpp v32, v32, v32 quad_perm:[1,0,3,2] row_mask:0xf bank_mask:0xf
	v_pk_fma_f32 v[26:27], v[182:183], v[10:11], v[26:27] op_sel_hi:[1,0,1]
	v_add_f32_dpp v28, v28, v28 quad_perm:[2,3,0,1] row_mask:0xf bank_mask:0xf
	v_add_f32_dpp v32, v32, v32 quad_perm:[2,3,0,1] row_mask:0xf bank_mask:0xf
	ds_read_b64 v[4:5], v196 offset:15360
	ds_read_b32 v6, v36 offset:15360
	v_add_f32_e32 v39, v32, v9
	v_mov_b32_dpp v30, v28 row_half_mirror row_mask:0xf bank_mask:0xf
	v_pk_fma_f32 v[20:21], v[88:89], v[28:29], v[20:21] op_sel_hi:[1,0,1] neg_lo:[0,1,0] neg_hi:[0,1,0]
	v_pk_fma_f32 v[22:23], v[90:91], v[28:29], v[22:23] op_sel_hi:[1,0,1] neg_lo:[0,1,0] neg_hi:[0,1,0]
	v_pk_fma_f32 v[24:25], v[88:89], v[30:31], v[24:25] op_sel_hi:[1,0,1] neg_lo:[0,1,0] neg_hi:[0,1,0]
	v_pk_fma_f32 v[26:27], v[90:91], v[30:31], v[26:27] op_sel_hi:[1,0,1] neg_lo:[0,1,0] neg_hi:[0,1,0]
	ds_write_b32 v102, v39 offset:3712
	ds_read_b128 v[144:147], v195 offset:7936
	ds_read_b128 v[156:159], v195 offset:16128
	ds_read_b128 v[168:171], v195 offset:32512
	ds_read_b128 v[180:183], v195 offset:24320
	ds_read_b128 v[88:91], v195 offset:40704
	s_waitcnt lgkmcnt(6)
	v_pk_mul_f32 v[46:47], v[24:25], v[140:141] op_sel_hi:[0,1]
	v_pk_mul_f32 v[34:35], v[20:21], v[140:141] op_sel_hi:[0,1]
	v_pk_fma_f32 v[46:47], v[24:25], v[142:143], v[46:47] op_sel:[1,0,0] op_sel_hi:[1,1,1]
	v_pk_fma_f32 v[34:35], v[20:21], v[142:143], v[34:35] op_sel:[1,0,0] op_sel_hi:[1,1,1]
	v_pk_fma_f32 v[46:47], v[26:27], v[152:153], v[46:47] op_sel_hi:[0,1,1]
	v_pk_fma_f32 v[34:35], v[22:23], v[152:153], v[34:35] op_sel_hi:[0,1,1]
	v_pk_fma_f32 v[46:47], v[26:27], v[154:155], v[46:47] op_sel:[1,0,0] op_sel_hi:[1,1,1]
	v_pk_fma_f32 v[34:35], v[22:23], v[154:155], v[34:35] op_sel:[1,0,0] op_sel_hi:[1,1,1]
	v_pk_fma_f32 v[20:21], v[176:177], v[4:5], v[20:21] op_sel_hi:[1,0,1]
	v_add_f32_dpp v28, v46, v34 row_half_mirror row_mask:0xf bank_mask:0xf
	v_add_f32_dpp v32, v47, v35 row_half_mirror row_mask:0xf bank_mask:0xf
	v_pk_fma_f32 v[22:23], v[178:179], v[4:5], v[22:23] op_sel_hi:[1,0,1]
	v_add_f32_dpp v28, v28, v28 row_ror:8 row_mask:0xf bank_mask:0xf
	v_add_f32_dpp v32, v32, v32 row_ror:8 row_mask:0xf bank_mask:0xf
	v_pk_fma_f32 v[24:25], v[176:177], v[6:7], v[24:25] op_sel_hi:[1,0,1]
	v_add_f32_dpp v28, v28, v28 quad_perm:[1,0,3,2] row_mask:0xf bank_mask:0xf
	v_add_f32_dpp v32, v32, v32 quad_perm:[1,0,3,2] row_mask:0xf bank_mask:0xf
	v_pk_fma_f32 v[26:27], v[178:179], v[6:7], v[26:27] op_sel_hi:[1,0,1]
	v_add_f32_dpp v28, v28, v28 quad_perm:[2,3,0,1] row_mask:0xf bank_mask:0xf
	v_add_f32_dpp v32, v32, v32 quad_perm:[2,3,0,1] row_mask:0xf bank_mask:0xf
	ds_read_b64 v[8:9], v196 offset:15872
	ds_read_b32 v10, v36 offset:15872
	v_add_f32_e32 v39, v32, v5
	v_mov_b32_dpp v30, v28 row_half_mirror row_mask:0xf bank_mask:0xf
	v_pk_fma_f32 v[20:21], v[84:85], v[28:29], v[20:21] op_sel_hi:[1,0,1] neg_lo:[0,1,0] neg_hi:[0,1,0]
	v_pk_fma_f32 v[22:23], v[86:87], v[28:29], v[22:23] op_sel_hi:[1,0,1] neg_lo:[0,1,0] neg_hi:[0,1,0]
	v_pk_fma_f32 v[24:25], v[84:85], v[30:31], v[24:25] op_sel_hi:[1,0,1] neg_lo:[0,1,0] neg_hi:[0,1,0]
	v_pk_fma_f32 v[26:27], v[86:87], v[30:31], v[26:27] op_sel_hi:[1,0,1] neg_lo:[0,1,0] neg_hi:[0,1,0]
	ds_write_b32 v102, v39 offset:3840
	s_waitcnt lgkmcnt(1)
	v_pk_mul_f32 v[46:47], v[24:25], v[144:145] op_sel_hi:[0,1]
	v_pk_mul_f32 v[34:35], v[20:21], v[144:145] op_sel_hi:[0,1]
	v_pk_fma_f32 v[46:47], v[24:25], v[146:147], v[46:47] op_sel:[1,0,0] op_sel_hi:[1,1,1]
	v_pk_fma_f32 v[34:35], v[20:21], v[146:147], v[34:35] op_sel:[1,0,0] op_sel_hi:[1,1,1]
	v_pk_fma_f32 v[46:47], v[26:27], v[156:157], v[46:47] op_sel_hi:[0,1,1]
	v_pk_fma_f32 v[34:35], v[22:23], v[156:157], v[34:35] op_sel_hi:[0,1,1]
	v_pk_fma_f32 v[46:47], v[26:27], v[158:159], v[46:47] op_sel:[1,0,0] op_sel_hi:[1,1,1]
	v_pk_fma_f32 v[34:35], v[22:23], v[158:159], v[34:35] op_sel:[1,0,0] op_sel_hi:[1,1,1]
	v_pk_mul_f32 v[20:21], v[20:21], v[168:169]
	v_add_f32_dpp v28, v46, v34 row_half_mirror row_mask:0xf bank_mask:0xf
	v_add_f32_dpp v32, v47, v35 row_half_mirror row_mask:0xf bank_mask:0xf
	v_pk_mul_f32 v[22:23], v[22:23], v[170:171]
	v_add_f32_dpp v28, v28, v28 row_ror:8 row_mask:0xf bank_mask:0xf
	v_add_f32_dpp v32, v32, v32 row_ror:8 row_mask:0xf bank_mask:0xf
	v_pk_mul_f32 v[24:25], v[24:25], v[168:169]
	v_add_f32_dpp v28, v28, v28 quad_perm:[1,0,3,2] row_mask:0xf bank_mask:0xf
	v_add_f32_dpp v32, v32, v32 quad_perm:[1,0,3,2] row_mask:0xf bank_mask:0xf
	v_pk_mul_f32 v[26:27], v[26:27], v[170:171]
	v_add_f32_dpp v28, v28, v28 quad_perm:[2,3,0,1] row_mask:0xf bank_mask:0xf
	v_add_f32_dpp v32, v32, v32 quad_perm:[2,3,0,1] row_mask:0xf bank_mask:0xf
	v_pk_fma_f32 v[20:21], v[180:181], v[8:9], v[20:21] op_sel_hi:[1,0,1]
	v_mov_b32_dpp v30, v28 row_half_mirror row_mask:0xf bank_mask:0xf
	v_pk_fma_f32 v[22:23], v[182:183], v[8:9], v[22:23] op_sel_hi:[1,0,1]
	v_pk_fma_f32 v[24:25], v[180:181], v[10:11], v[24:25] op_sel_hi:[1,0,1]
	v_pk_fma_f32 v[26:27], v[182:183], v[10:11], v[26:27] op_sel_hi:[1,0,1]
	v_pk_fma_f32 v[20:21], v[88:89], v[28:29], v[20:21] op_sel_hi:[1,0,1] neg_lo:[0,1,0] neg_hi:[0,1,0]
	v_pk_fma_f32 v[22:23], v[90:91], v[28:29], v[22:23] op_sel_hi:[1,0,1] neg_lo:[0,1,0] neg_hi:[0,1,0]
	v_pk_fma_f32 v[24:25], v[88:89], v[30:31], v[24:25] op_sel_hi:[1,0,1] neg_lo:[0,1,0] neg_hi:[0,1,0]
	v_pk_fma_f32 v[26:27], v[90:91], v[30:31], v[26:27] op_sel_hi:[1,0,1] neg_lo:[0,1,0] neg_hi:[0,1,0]
	v_add_f32_e32 v39, v32, v9
	ds_write_b32 v102, v39 offset:3968
	s_waitcnt lgkmcnt(0)
	s_barrier
	s_add_i32 s8, s8, 1
	s_cmp_eq_u32 s8, 64
	s_cbranch_scc0 .Lrw_scan_loop
	s_setprio 0
	s_branch .LBB0_183
